# v100 + GEMM1 epilogue output stores marked nt (non-temporal) so L2 keeps the A/B panels
# speedup vs baseline: 1.0180x; 1.0090x over previous
.Lxb_p1_a:
	v_lshl_add_u32 v174, s30, 8, v1
	s_cmp_gt_i32 s12, 3
	s_mov_b64 s[34:35], -1
	s_cbranch_scc0 .LBB0_204
	s_cmp_gt_u32 s12, 7
	s_cbranch_scc0 .LBB0_201
	s_cmp_lt_u32 s12, 16
	s_cbranch_scc0 .LBB0_193
	s_add_i32 s14, s12, -8
	v_lshl_or_b32 v158, s14, 8, v160
	v_lshl_add_u64 v[134:135], v[158:159], 2, s[70:71]
	global_load_dwordx4 v[138:141], v[134:135], off offset:16
	global_load_dwordx4 v[142:145], v[134:135], off
	global_load_dwordx4 v[130:133], v[134:135], off offset:528
	s_nop 0
	global_load_dwordx4 v[134:137], v[134:135], off offset:512
	s_lshl_b32 s15, s30, 3
	s_add_i32 s14, s15, s14
	s_ashr_i32 s15, s14, 31
	s_lshl_b64 s[14:15], s[14:15], 17
	v_readlane_b32 s16, v254, 9
	s_add_u32 s30, s16, s14
	v_readlane_b32 s14, v254, 10
	s_addc_u32 s31, s14, s15
	v_mov_b32_e32 v173, v159
	v_lshl_add_u64 v[176:177], s[30:31], 0, v[172:173]
	s_mov_b64 s[34:35], 0
	s_mov_b32 s14, 0x1000
	s_mov_b32 s15, 0
	s_mov_b32 s100, 0xbfb8aa3b
	s_mov_b32 s101, 0xbfb8aa3b
	s_waitcnt vmcnt(0)
	v_pk_mul_f32 v[130:131], v[130:131], s[100:101]
	v_pk_mul_f32 v[132:133], v[132:133], s[100:101]
	v_pk_mul_f32 v[134:135], v[134:135], s[100:101]
	v_pk_mul_f32 v[136:137], v[136:137], s[100:101]
	v_pk_mul_f32 v[138:139], v[138:139], s[100:101]
	v_pk_mul_f32 v[140:141], v[140:141], s[100:101]
	v_pk_mul_f32 v[142:143], v[142:143], s[100:101]
	v_pk_mul_f32 v[144:145], v[144:145], s[100:101]
	v_pk_fma_f32 v[126:127], v[126:127], s[100:101], v[142:143]
	v_pk_fma_f32 v[128:129], v[128:129], s[100:101], v[144:145]
	v_pk_fma_f32 v[122:123], v[122:123], s[100:101], v[138:139]
	v_pk_fma_f32 v[124:125], v[124:125], s[100:101], v[140:141]
	v_exp_f32_e32 v126, v126
	v_exp_f32_e32 v127, v127
	v_exp_f32_e32 v128, v128
	v_exp_f32_e32 v129, v129
	v_exp_f32_e32 v122, v122
	v_exp_f32_e32 v123, v123
	v_exp_f32_e32 v124, v124
	v_exp_f32_e32 v125, v125
	v_pk_add_f32 v[126:127], v[126:127], 1.0 op_sel_hi:[1,0]
	v_pk_add_f32 v[128:129], v[128:129], 1.0 op_sel_hi:[1,0]
	v_pk_add_f32 v[122:123], v[122:123], 1.0 op_sel_hi:[1,0]
	v_pk_add_f32 v[124:125], v[124:125], 1.0 op_sel_hi:[1,0]
	v_rcp_f32_e32 v126, v126
	v_rcp_f32_e32 v127, v127
	v_rcp_f32_e32 v128, v128
	v_rcp_f32_e32 v129, v129
	v_rcp_f32_e32 v122, v122
	v_rcp_f32_e32 v123, v123
	v_rcp_f32_e32 v124, v124
	v_rcp_f32_e32 v125, v125
	v_cvt_pk_bf16_f32 v146, v126, v127
	v_cvt_pk_bf16_f32 v147, v128, v129
	v_cvt_pk_bf16_f32 v148, v122, v123
	v_cvt_pk_bf16_f32 v149, v124, v125
	global_store_dwordx4 v[176:177], v[146:149], off offset:0 nt
	v_pk_fma_f32 v[118:119], v[118:119], s[100:101], v[134:135]
	v_pk_fma_f32 v[120:121], v[120:121], s[100:101], v[136:137]
	v_pk_fma_f32 v[114:115], v[114:115], s[100:101], v[130:131]
	v_pk_fma_f32 v[116:117], v[116:117], s[100:101], v[132:133]
	v_exp_f32_e32 v118, v118
	v_exp_f32_e32 v119, v119
	v_exp_f32_e32 v120, v120
	v_exp_f32_e32 v121, v121
	v_exp_f32_e32 v114, v114
	v_exp_f32_e32 v115, v115
	v_exp_f32_e32 v116, v116
	v_exp_f32_e32 v117, v117
	v_pk_add_f32 v[118:119], v[118:119], 1.0 op_sel_hi:[1,0]
	v_pk_add_f32 v[120:121], v[120:121], 1.0 op_sel_hi:[1,0]
	v_pk_add_f32 v[114:115], v[114:115], 1.0 op_sel_hi:[1,0]
	v_pk_add_f32 v[116:117], v[116:117], 1.0 op_sel_hi:[1,0]
	v_rcp_f32_e32 v118, v118
	v_rcp_f32_e32 v119, v119
	v_rcp_f32_e32 v120, v120
	v_rcp_f32_e32 v121, v121
	v_rcp_f32_e32 v114, v114
	v_rcp_f32_e32 v115, v115
	v_rcp_f32_e32 v116, v116
	v_rcp_f32_e32 v117, v117
	v_cvt_pk_bf16_f32 v182, v118, v119
	v_cvt_pk_bf16_f32 v183, v120, v121
	v_cvt_pk_bf16_f32 v184, v114, v115
	v_cvt_pk_bf16_f32 v185, v116, v117
	global_store_dwordx4 v[176:177], v[182:185], off offset:1024 nt
	v_pk_fma_f32 v[110:111], v[110:111], s[100:101], v[142:143]
	v_pk_fma_f32 v[112:113], v[112:113], s[100:101], v[144:145]
	v_pk_fma_f32 v[106:107], v[106:107], s[100:101], v[138:139]
	v_pk_fma_f32 v[108:109], v[108:109], s[100:101], v[140:141]
	v_exp_f32_e32 v110, v110
	v_exp_f32_e32 v111, v111
	v_exp_f32_e32 v112, v112
	v_exp_f32_e32 v113, v113
	v_exp_f32_e32 v106, v106
	v_exp_f32_e32 v107, v107
	v_exp_f32_e32 v108, v108
	v_exp_f32_e32 v109, v109
	v_pk_add_f32 v[110:111], v[110:111], 1.0 op_sel_hi:[1,0]
	v_pk_add_f32 v[112:113], v[112:113], 1.0 op_sel_hi:[1,0]
	v_pk_add_f32 v[106:107], v[106:107], 1.0 op_sel_hi:[1,0]
	v_pk_add_f32 v[108:109], v[108:109], 1.0 op_sel_hi:[1,0]
	v_rcp_f32_e32 v110, v110
	v_rcp_f32_e32 v111, v111
	v_rcp_f32_e32 v112, v112
	v_rcp_f32_e32 v113, v113
	v_rcp_f32_e32 v106, v106
	v_rcp_f32_e32 v107, v107
	v_rcp_f32_e32 v108, v108
	v_rcp_f32_e32 v109, v109
	v_cvt_pk_bf16_f32 v146, v110, v111
	v_cvt_pk_bf16_f32 v147, v112, v113
	v_cvt_pk_bf16_f32 v148, v106, v107
	v_cvt_pk_bf16_f32 v149, v108, v109
	global_store_dwordx4 v[176:177], v[146:149], off offset:2048 nt
	v_pk_fma_f32 v[102:103], v[102:103], s[100:101], v[134:135]
	v_pk_fma_f32 v[104:105], v[104:105], s[100:101], v[136:137]
	v_pk_fma_f32 v[98:99], v[98:99], s[100:101], v[130:131]
	v_pk_fma_f32 v[100:101], v[100:101], s[100:101], v[132:133]
	v_exp_f32_e32 v102, v102
	v_exp_f32_e32 v103, v103
	v_exp_f32_e32 v104, v104
	v_exp_f32_e32 v105, v105
	v_exp_f32_e32 v98, v98
	v_exp_f32_e32 v99, v99
	v_exp_f32_e32 v100, v100
	v_exp_f32_e32 v101, v101
	v_pk_add_f32 v[102:103], v[102:103], 1.0 op_sel_hi:[1,0]
	v_pk_add_f32 v[104:105], v[104:105], 1.0 op_sel_hi:[1,0]
	v_pk_add_f32 v[98:99], v[98:99], 1.0 op_sel_hi:[1,0]
	v_pk_add_f32 v[100:101], v[100:101], 1.0 op_sel_hi:[1,0]
	v_rcp_f32_e32 v102, v102
	v_rcp_f32_e32 v103, v103
	v_rcp_f32_e32 v104, v104
	v_rcp_f32_e32 v105, v105
	v_rcp_f32_e32 v98, v98
	v_rcp_f32_e32 v99, v99
	v_rcp_f32_e32 v100, v100
	v_rcp_f32_e32 v101, v101
	v_cvt_pk_bf16_f32 v182, v102, v103
	v_cvt_pk_bf16_f32 v183, v104, v105
	v_cvt_pk_bf16_f32 v184, v98, v99
	v_cvt_pk_bf16_f32 v185, v100, v101
	global_store_dwordx4 v[176:177], v[182:185], off offset:3072 nt
	v_lshl_add_u64 v[176:177], v[176:177], 0, s[14:15]
	v_pk_fma_f32 v[94:95], v[94:95], s[100:101], v[142:143]
	v_pk_fma_f32 v[96:97], v[96:97], s[100:101], v[144:145]
	v_pk_fma_f32 v[90:91], v[90:91], s[100:101], v[138:139]
	v_pk_fma_f32 v[92:93], v[92:93], s[100:101], v[140:141]
	v_exp_f32_e32 v94, v94
	v_exp_f32_e32 v95, v95
	v_exp_f32_e32 v96, v96
	v_exp_f32_e32 v97, v97
	v_exp_f32_e32 v90, v90
	v_exp_f32_e32 v91, v91
	v_exp_f32_e32 v92, v92
	v_exp_f32_e32 v93, v93
	v_pk_add_f32 v[94:95], v[94:95], 1.0 op_sel_hi:[1,0]
	v_pk_add_f32 v[96:97], v[96:97], 1.0 op_sel_hi:[1,0]
	v_pk_add_f32 v[90:91], v[90:91], 1.0 op_sel_hi:[1,0]
	v_pk_add_f32 v[92:93], v[92:93], 1.0 op_sel_hi:[1,0]
	v_rcp_f32_e32 v94, v94
	v_rcp_f32_e32 v95, v95
	v_rcp_f32_e32 v96, v96
	v_rcp_f32_e32 v97, v97
	v_rcp_f32_e32 v90, v90
	v_rcp_f32_e32 v91, v91
	v_rcp_f32_e32 v92, v92
	v_rcp_f32_e32 v93, v93
	v_cvt_pk_bf16_f32 v146, v94, v95
	v_cvt_pk_bf16_f32 v147, v96, v97
	v_cvt_pk_bf16_f32 v148, v90, v91
	v_cvt_pk_bf16_f32 v149, v92, v93
	global_store_dwordx4 v[176:177], v[146:149], off offset:0 nt
	v_pk_fma_f32 v[86:87], v[86:87], s[100:101], v[134:135]
	v_pk_fma_f32 v[88:89], v[88:89], s[100:101], v[136:137]
	v_pk_fma_f32 v[82:83], v[82:83], s[100:101], v[130:131]
	v_pk_fma_f32 v[84:85], v[84:85], s[100:101], v[132:133]
	v_exp_f32_e32 v86, v86
	v_exp_f32_e32 v87, v87
	v_exp_f32_e32 v88, v88
	v_exp_f32_e32 v89, v89
	v_exp_f32_e32 v82, v82
	v_exp_f32_e32 v83, v83
	v_exp_f32_e32 v84, v84
	v_exp_f32_e32 v85, v85
	v_pk_add_f32 v[86:87], v[86:87], 1.0 op_sel_hi:[1,0]
	v_pk_add_f32 v[88:89], v[88:89], 1.0 op_sel_hi:[1,0]
	v_pk_add_f32 v[82:83], v[82:83], 1.0 op_sel_hi:[1,0]
	v_pk_add_f32 v[84:85], v[84:85], 1.0 op_sel_hi:[1,0]
	v_rcp_f32_e32 v86, v86
	v_rcp_f32_e32 v87, v87
	v_rcp_f32_e32 v88, v88
	v_rcp_f32_e32 v89, v89
	v_rcp_f32_e32 v82, v82
	v_rcp_f32_e32 v83, v83
	v_rcp_f32_e32 v84, v84
	v_rcp_f32_e32 v85, v85
	v_cvt_pk_bf16_f32 v182, v86, v87
	v_cvt_pk_bf16_f32 v183, v88, v89
	v_cvt_pk_bf16_f32 v184, v82, v83
	v_cvt_pk_bf16_f32 v185, v84, v85
	global_store_dwordx4 v[176:177], v[182:185], off offset:1024 nt
	v_pk_fma_f32 v[78:79], v[78:79], s[100:101], v[142:143]
	v_pk_fma_f32 v[80:81], v[80:81], s[100:101], v[144:145]
	v_pk_fma_f32 v[74:75], v[74:75], s[100:101], v[138:139]
	v_pk_fma_f32 v[76:77], v[76:77], s[100:101], v[140:141]
	v_exp_f32_e32 v78, v78
	v_exp_f32_e32 v79, v79
	v_exp_f32_e32 v80, v80
	v_exp_f32_e32 v81, v81
	v_exp_f32_e32 v74, v74
	v_exp_f32_e32 v75, v75
	v_exp_f32_e32 v76, v76
	v_exp_f32_e32 v77, v77
	v_pk_add_f32 v[78:79], v[78:79], 1.0 op_sel_hi:[1,0]
	v_pk_add_f32 v[80:81], v[80:81], 1.0 op_sel_hi:[1,0]
	v_pk_add_f32 v[74:75], v[74:75], 1.0 op_sel_hi:[1,0]
	v_pk_add_f32 v[76:77], v[76:77], 1.0 op_sel_hi:[1,0]
	v_rcp_f32_e32 v78, v78
	v_rcp_f32_e32 v79, v79
	v_rcp_f32_e32 v80, v80
	v_rcp_f32_e32 v81, v81
	v_rcp_f32_e32 v74, v74
	v_rcp_f32_e32 v75, v75
	v_rcp_f32_e32 v76, v76
	v_rcp_f32_e32 v77, v77
	v_cvt_pk_bf16_f32 v146, v78, v79
	v_cvt_pk_bf16_f32 v147, v80, v81
	v_cvt_pk_bf16_f32 v148, v74, v75
	v_cvt_pk_bf16_f32 v149, v76, v77
	global_store_dwordx4 v[176:177], v[146:149], off offset:2048 nt
	v_pk_fma_f32 v[70:71], v[70:71], s[100:101], v[134:135]
	v_pk_fma_f32 v[72:73], v[72:73], s[100:101], v[136:137]
	v_pk_fma_f32 v[66:67], v[66:67], s[100:101], v[130:131]
	v_pk_fma_f32 v[68:69], v[68:69], s[100:101], v[132:133]
	v_exp_f32_e32 v70, v70
	v_exp_f32_e32 v71, v71
	v_exp_f32_e32 v72, v72
	v_exp_f32_e32 v73, v73
	v_exp_f32_e32 v66, v66
	v_exp_f32_e32 v67, v67
	v_exp_f32_e32 v68, v68
	v_exp_f32_e32 v69, v69
	v_pk_add_f32 v[70:71], v[70:71], 1.0 op_sel_hi:[1,0]
	v_pk_add_f32 v[72:73], v[72:73], 1.0 op_sel_hi:[1,0]
	v_pk_add_f32 v[66:67], v[66:67], 1.0 op_sel_hi:[1,0]
	v_pk_add_f32 v[68:69], v[68:69], 1.0 op_sel_hi:[1,0]
	v_rcp_f32_e32 v70, v70
	v_rcp_f32_e32 v71, v71
	v_rcp_f32_e32 v72, v72
	v_rcp_f32_e32 v73, v73
	v_rcp_f32_e32 v66, v66
	v_rcp_f32_e32 v67, v67
	v_rcp_f32_e32 v68, v68
	v_rcp_f32_e32 v69, v69
	v_cvt_pk_bf16_f32 v182, v70, v71
	v_cvt_pk_bf16_f32 v183, v72, v73
	v_cvt_pk_bf16_f32 v184, v66, v67
	v_cvt_pk_bf16_f32 v185, v68, v69
	global_store_dwordx4 v[176:177], v[182:185], off offset:3072 nt
	v_lshl_add_u64 v[176:177], v[176:177], 0, s[14:15]
	v_pk_fma_f32 v[62:63], v[62:63], s[100:101], v[142:143]
	v_pk_fma_f32 v[64:65], v[64:65], s[100:101], v[144:145]
	v_pk_fma_f32 v[58:59], v[58:59], s[100:101], v[138:139]
	v_pk_fma_f32 v[60:61], v[60:61], s[100:101], v[140:141]
	v_exp_f32_e32 v62, v62
	v_exp_f32_e32 v63, v63
	v_exp_f32_e32 v64, v64
	v_exp_f32_e32 v65, v65
	v_exp_f32_e32 v58, v58
	v_exp_f32_e32 v59, v59
	v_exp_f32_e32 v60, v60
	v_exp_f32_e32 v61, v61
	v_pk_add_f32 v[62:63], v[62:63], 1.0 op_sel_hi:[1,0]
	v_pk_add_f32 v[64:65], v[64:65], 1.0 op_sel_hi:[1,0]
	v_pk_add_f32 v[58:59], v[58:59], 1.0 op_sel_hi:[1,0]
	v_pk_add_f32 v[60:61], v[60:61], 1.0 op_sel_hi:[1,0]
	v_rcp_f32_e32 v62, v62
	v_rcp_f32_e32 v63, v63
	v_rcp_f32_e32 v64, v64
	v_rcp_f32_e32 v65, v65
	v_rcp_f32_e32 v58, v58
	v_rcp_f32_e32 v59, v59
	v_rcp_f32_e32 v60, v60
	v_rcp_f32_e32 v61, v61
	v_cvt_pk_bf16_f32 v146, v62, v63
	v_cvt_pk_bf16_f32 v147, v64, v65
	v_cvt_pk_bf16_f32 v148, v58, v59
	v_cvt_pk_bf16_f32 v149, v60, v61
	global_store_dwordx4 v[176:177], v[146:149], off offset:0 nt
	v_pk_fma_f32 v[54:55], v[54:55], s[100:101], v[134:135]
	v_pk_fma_f32 v[56:57], v[56:57], s[100:101], v[136:137]
	v_pk_fma_f32 v[50:51], v[50:51], s[100:101], v[130:131]
	v_pk_fma_f32 v[52:53], v[52:53], s[100:101], v[132:133]
	v_exp_f32_e32 v54, v54
	v_exp_f32_e32 v55, v55
	v_exp_f32_e32 v56, v56
	v_exp_f32_e32 v57, v57
	v_exp_f32_e32 v50, v50
	v_exp_f32_e32 v51, v51
	v_exp_f32_e32 v52, v52
	v_exp_f32_e32 v53, v53
	v_pk_add_f32 v[54:55], v[54:55], 1.0 op_sel_hi:[1,0]
	v_pk_add_f32 v[56:57], v[56:57], 1.0 op_sel_hi:[1,0]
	v_pk_add_f32 v[50:51], v[50:51], 1.0 op_sel_hi:[1,0]
	v_pk_add_f32 v[52:53], v[52:53], 1.0 op_sel_hi:[1,0]
	v_rcp_f32_e32 v54, v54
	v_rcp_f32_e32 v55, v55
	v_rcp_f32_e32 v56, v56
	v_rcp_f32_e32 v57, v57
	v_rcp_f32_e32 v50, v50
	v_rcp_f32_e32 v51, v51
	v_rcp_f32_e32 v52, v52
	v_rcp_f32_e32 v53, v53
	v_cvt_pk_bf16_f32 v182, v54, v55
	v_cvt_pk_bf16_f32 v183, v56, v57
	v_cvt_pk_bf16_f32 v184, v50, v51
	v_cvt_pk_bf16_f32 v185, v52, v53
	global_store_dwordx4 v[176:177], v[182:185], off offset:1024 nt
	v_pk_fma_f32 v[46:47], v[46:47], s[100:101], v[142:143]
	v_pk_fma_f32 v[48:49], v[48:49], s[100:101], v[144:145]
	v_pk_fma_f32 v[42:43], v[42:43], s[100:101], v[138:139]
	v_pk_fma_f32 v[44:45], v[44:45], s[100:101], v[140:141]
	v_exp_f32_e32 v46, v46
	v_exp_f32_e32 v47, v47
	v_exp_f32_e32 v48, v48
	v_exp_f32_e32 v49, v49
	v_exp_f32_e32 v42, v42
	v_exp_f32_e32 v43, v43
	v_exp_f32_e32 v44, v44
	v_exp_f32_e32 v45, v45
	v_pk_add_f32 v[46:47], v[46:47], 1.0 op_sel_hi:[1,0]
	v_pk_add_f32 v[48:49], v[48:49], 1.0 op_sel_hi:[1,0]
	v_pk_add_f32 v[42:43], v[42:43], 1.0 op_sel_hi:[1,0]
	v_pk_add_f32 v[44:45], v[44:45], 1.0 op_sel_hi:[1,0]
	v_rcp_f32_e32 v46, v46
	v_rcp_f32_e32 v47, v47
	v_rcp_f32_e32 v48, v48
	v_rcp_f32_e32 v49, v49
	v_rcp_f32_e32 v42, v42
	v_rcp_f32_e32 v43, v43
	v_rcp_f32_e32 v44, v44
	v_rcp_f32_e32 v45, v45
	v_cvt_pk_bf16_f32 v146, v46, v47
	v_cvt_pk_bf16_f32 v147, v48, v49
	v_cvt_pk_bf16_f32 v148, v42, v43
	v_cvt_pk_bf16_f32 v149, v44, v45
	global_store_dwordx4 v[176:177], v[146:149], off offset:2048 nt
	v_pk_fma_f32 v[38:39], v[38:39], s[100:101], v[134:135]
	v_pk_fma_f32 v[40:41], v[40:41], s[100:101], v[136:137]
	v_pk_fma_f32 v[34:35], v[34:35], s[100:101], v[130:131]
	v_pk_fma_f32 v[36:37], v[36:37], s[100:101], v[132:133]
	v_exp_f32_e32 v38, v38
	v_exp_f32_e32 v39, v39
	v_exp_f32_e32 v40, v40
	v_exp_f32_e32 v41, v41
	v_exp_f32_e32 v34, v34
	v_exp_f32_e32 v35, v35
	v_exp_f32_e32 v36, v36
	v_exp_f32_e32 v37, v37
	v_pk_add_f32 v[38:39], v[38:39], 1.0 op_sel_hi:[1,0]
	v_pk_add_f32 v[40:41], v[40:41], 1.0 op_sel_hi:[1,0]
	v_pk_add_f32 v[34:35], v[34:35], 1.0 op_sel_hi:[1,0]
	v_pk_add_f32 v[36:37], v[36:37], 1.0 op_sel_hi:[1,0]
	v_rcp_f32_e32 v38, v38
	v_rcp_f32_e32 v39, v39
	v_rcp_f32_e32 v40, v40
	v_rcp_f32_e32 v41, v41
	v_rcp_f32_e32 v34, v34
	v_rcp_f32_e32 v35, v35
	v_rcp_f32_e32 v36, v36
	v_rcp_f32_e32 v37, v37
	v_cvt_pk_bf16_f32 v182, v38, v39
	v_cvt_pk_bf16_f32 v183, v40, v41
	v_cvt_pk_bf16_f32 v184, v34, v35
	v_cvt_pk_bf16_f32 v185, v36, v37
	global_store_dwordx4 v[176:177], v[182:185], off offset:3072 nt
	v_lshl_add_u64 v[176:177], v[176:177], 0, s[14:15]
	v_pk_fma_f32 v[30:31], v[30:31], s[100:101], v[142:143]
	v_pk_fma_f32 v[32:33], v[32:33], s[100:101], v[144:145]
	v_pk_fma_f32 v[26:27], v[26:27], s[100:101], v[138:139]
	v_pk_fma_f32 v[28:29], v[28:29], s[100:101], v[140:141]
	v_exp_f32_e32 v30, v30
	v_exp_f32_e32 v31, v31
	v_exp_f32_e32 v32, v32
	v_exp_f32_e32 v33, v33
	v_exp_f32_e32 v26, v26
	v_exp_f32_e32 v27, v27
	v_exp_f32_e32 v28, v28
	v_exp_f32_e32 v29, v29
	v_pk_add_f32 v[30:31], v[30:31], 1.0 op_sel_hi:[1,0]
	v_pk_add_f32 v[32:33], v[32:33], 1.0 op_sel_hi:[1,0]
	v_pk_add_f32 v[26:27], v[26:27], 1.0 op_sel_hi:[1,0]
	v_pk_add_f32 v[28:29], v[28:29], 1.0 op_sel_hi:[1,0]
	v_rcp_f32_e32 v30, v30
	v_rcp_f32_e32 v31, v31
	v_rcp_f32_e32 v32, v32
	v_rcp_f32_e32 v33, v33
	v_rcp_f32_e32 v26, v26
	v_rcp_f32_e32 v27, v27
	v_rcp_f32_e32 v28, v28
	v_rcp_f32_e32 v29, v29
	v_cvt_pk_bf16_f32 v146, v30, v31
	v_cvt_pk_bf16_f32 v147, v32, v33
	v_cvt_pk_bf16_f32 v148, v26, v27
	v_cvt_pk_bf16_f32 v149, v28, v29
	global_store_dwordx4 v[176:177], v[146:149], off offset:0 nt
	v_pk_fma_f32 v[22:23], v[22:23], s[100:101], v[134:135]
	v_pk_fma_f32 v[24:25], v[24:25], s[100:101], v[136:137]
	v_pk_fma_f32 v[18:19], v[18:19], s[100:101], v[130:131]
	v_pk_fma_f32 v[20:21], v[20:21], s[100:101], v[132:133]
	v_exp_f32_e32 v22, v22
	v_exp_f32_e32 v23, v23
	v_exp_f32_e32 v24, v24
	v_exp_f32_e32 v25, v25
	v_exp_f32_e32 v18, v18
	v_exp_f32_e32 v19, v19
	v_exp_f32_e32 v20, v20
	v_exp_f32_e32 v21, v21
	v_pk_add_f32 v[22:23], v[22:23], 1.0 op_sel_hi:[1,0]
	v_pk_add_f32 v[24:25], v[24:25], 1.0 op_sel_hi:[1,0]
	v_pk_add_f32 v[18:19], v[18:19], 1.0 op_sel_hi:[1,0]
	v_pk_add_f32 v[20:21], v[20:21], 1.0 op_sel_hi:[1,0]
	v_rcp_f32_e32 v22, v22
	v_rcp_f32_e32 v23, v23
	v_rcp_f32_e32 v24, v24
	v_rcp_f32_e32 v25, v25
	v_rcp_f32_e32 v18, v18
	v_rcp_f32_e32 v19, v19
	v_rcp_f32_e32 v20, v20
	v_rcp_f32_e32 v21, v21
	v_cvt_pk_bf16_f32 v182, v22, v23
	v_cvt_pk_bf16_f32 v183, v24, v25
	v_cvt_pk_bf16_f32 v184, v18, v19
	v_cvt_pk_bf16_f32 v185, v20, v21
	global_store_dwordx4 v[176:177], v[182:185], off offset:1024 nt
	v_pk_fma_f32 v[14:15], v[14:15], s[100:101], v[142:143]
	v_pk_fma_f32 v[16:17], v[16:17], s[100:101], v[144:145]
	v_pk_fma_f32 v[10:11], v[10:11], s[100:101], v[138:139]
	v_pk_fma_f32 v[12:13], v[12:13], s[100:101], v[140:141]
	v_exp_f32_e32 v14, v14
	v_exp_f32_e32 v15, v15
	v_exp_f32_e32 v16, v16
	v_exp_f32_e32 v17, v17
	v_exp_f32_e32 v10, v10
	v_exp_f32_e32 v11, v11
	v_exp_f32_e32 v12, v12
	v_exp_f32_e32 v13, v13
	v_pk_add_f32 v[14:15], v[14:15], 1.0 op_sel_hi:[1,0]
	v_pk_add_f32 v[16:17], v[16:17], 1.0 op_sel_hi:[1,0]
	v_pk_add_f32 v[10:11], v[10:11], 1.0 op_sel_hi:[1,0]
	v_pk_add_f32 v[12:13], v[12:13], 1.0 op_sel_hi:[1,0]
	v_rcp_f32_e32 v14, v14
	v_rcp_f32_e32 v15, v15
	v_rcp_f32_e32 v16, v16
	v_rcp_f32_e32 v17, v17
	v_rcp_f32_e32 v10, v10
	v_rcp_f32_e32 v11, v11
	v_rcp_f32_e32 v12, v12
	v_rcp_f32_e32 v13, v13
	v_cvt_pk_bf16_f32 v146, v14, v15
	v_cvt_pk_bf16_f32 v147, v16, v17
	v_cvt_pk_bf16_f32 v148, v10, v11
	v_cvt_pk_bf16_f32 v149, v12, v13
	global_store_dwordx4 v[176:177], v[146:149], off offset:2048 nt
	v_pk_fma_f32 v[6:7], v[6:7], s[100:101], v[134:135]
	v_pk_fma_f32 v[8:9], v[8:9], s[100:101], v[136:137]
	v_pk_fma_f32 v[2:3], v[2:3], s[100:101], v[130:131]
	v_pk_fma_f32 v[4:5], v[4:5], s[100:101], v[132:133]
	v_exp_f32_e32 v6, v6
	v_exp_f32_e32 v7, v7
	v_exp_f32_e32 v8, v8
	v_exp_f32_e32 v9, v9
	v_exp_f32_e32 v2, v2
	v_exp_f32_e32 v3, v3
	v_exp_f32_e32 v4, v4
	v_exp_f32_e32 v5, v5
	v_pk_add_f32 v[6:7], v[6:7], 1.0 op_sel_hi:[1,0]
	v_pk_add_f32 v[8:9], v[8:9], 1.0 op_sel_hi:[1,0]
	v_pk_add_f32 v[2:3], v[2:3], 1.0 op_sel_hi:[1,0]
	v_pk_add_f32 v[4:5], v[4:5], 1.0 op_sel_hi:[1,0]
	v_rcp_f32_e32 v6, v6
	v_rcp_f32_e32 v7, v7
	v_rcp_f32_e32 v8, v8
	v_rcp_f32_e32 v9, v9
	v_rcp_f32_e32 v2, v2
	v_rcp_f32_e32 v3, v3
	v_rcp_f32_e32 v4, v4
	v_rcp_f32_e32 v5, v5
	v_cvt_pk_bf16_f32 v182, v6, v7
	v_cvt_pk_bf16_f32 v183, v8, v9
	v_cvt_pk_bf16_f32 v184, v2, v3
	v_cvt_pk_bf16_f32 v185, v4, v5
	global_store_dwordx4 v[176:177], v[182:185], off offset:3072 nt
	s_branch .LBB0_184
.LBB0_193:
	s_andn2_b64 vcc, exec, s[34:35]
	s_cbranch_vccnz .LBB0_200
	s_cmp_gt_u32 s12, 21
	s_mov_b64 s[30:31], -1
	s_cbranch_scc0 .LBB0_198
	v_readlane_b32 s14, v254, 7
	v_readlane_b32 s15, v254, 8
	s_andn2_b64 vcc, exec, s[14:15]
	s_cbranch_vccnz .LBB0_197
	v_or_b32_e32 v132, 16, v174
	v_ashrrev_i32_e32 v175, 31, v174
	v_ashrrev_i32_e32 v133, 31, v132
	v_lshlrev_b64 v[130:131], 7, v[174:175]
	v_lshlrev_b64 v[132:133], 7, v[132:133]
	v_lshl_add_u64 v[130:131], v[162:163], 0, v[130:131]
	v_lshl_add_u64 v[132:133], v[162:163], 0, v[132:133]
	global_store_dwordx4 v[130:131], v[126:129], off nt
	global_store_dwordx4 v[130:131], v[122:125], off offset:16 nt
	global_store_dwordx4 v[132:133], v[110:113], off nt
	global_store_dwordx4 v[132:133], v[106:109], off offset:16 nt
	v_or_b32_e32 v132, 32, v174
	v_ashrrev_i32_e32 v133, 31, v132
	v_lshlrev_b64 v[132:133], 7, v[132:133]
	v_lshl_add_u64 v[132:133], v[162:163], 0, v[132:133]
	global_store_dwordx4 v[132:133], v[94:97], off nt
	global_store_dwordx4 v[132:133], v[90:93], off offset:16 nt
	v_or_b32_e32 v132, 48, v174
	v_ashrrev_i32_e32 v133, 31, v132
	v_lshlrev_b64 v[132:133], 7, v[132:133]
	v_lshl_add_u64 v[132:133], v[162:163], 0, v[132:133]
	s_mov_b64 s[14:15], 0x4000
	global_store_dwordx4 v[132:133], v[78:81], off nt
	global_store_dwordx4 v[132:133], v[74:77], off offset:16 nt
	v_lshl_add_u64 v[132:133], v[130:131], 0, s[14:15]
	s_movk_i32 s14, 0x4000
	v_add_co_u32_e32 v134, vcc, s14, v130
	s_mov_b64 s[14:15], 0x4800
	s_nop 0
	v_addc_co_u32_e32 v135, vcc, 0, v131, vcc
	global_store_dwordx4 v[134:135], v[62:65], off nt
	global_store_dwordx4 v[132:133], v[58:61], off offset:16 nt
	v_lshl_add_u64 v[132:133], v[130:131], 0, s[14:15]
	global_store_dwordx4 v[134:135], v[46:49], off offset:2048 nt
	global_store_dwordx4 v[132:133], v[42:45], off offset:16 nt
	s_mov_b64 s[14:15], 0x5000
	v_add_co_u32_e32 v134, vcc, 0x5000, v130
	v_lshl_add_u64 v[132:133], v[130:131], 0, s[14:15]
	s_nop 0
	v_addc_co_u32_e32 v135, vcc, 0, v131, vcc
	s_mov_b64 s[14:15], 0x5800
	global_store_dwordx4 v[134:135], v[30:33], off nt
	global_store_dwordx4 v[132:133], v[26:29], off offset:16 nt
	v_lshl_add_u64 v[130:131], v[130:131], 0, s[14:15]
	global_store_dwordx4 v[134:135], v[14:17], off offset:2048 nt
	global_store_dwordx4 v[130:131], v[10:13], off offset:16 nt

.LBB0_198:
	s_andn2_b64 vcc, exec, s[30:31]
	s_cbranch_vccnz .LBB0_200
	s_cmp_lt_u32 s12, 20
	s_mov_b32 s14, 0xf800400
	s_cselect_b32 s14, s14, 0x11800400
	s_cmp_gt_u32 s12, 17
	s_cselect_b32 s14, s14, 0xd800400
	s_add_u32 s14, s62, s14
	s_addc_u32 s15, s63, 0
	s_lshl_b32 s16, s12, 9
	s_and_b32 s16, s16, 0x200
	s_add_u32 s14, s14, s16
	s_addc_u32 s15, s15, 0
	v_lshlrev_b32_e32 v158, 1, v160
	v_ashrrev_i32_e32 v175, 31, v174
	v_lshl_add_u64 v[134:135], s[14:15], 0, v[158:159]
	v_lshlrev_b64 v[130:131], 10, v[174:175]
	v_lshl_add_u64 v[136:137], v[134:135], 0, v[130:131]
	v_cvt_pk_bf16_f32 v130, v126, v127
	v_cvt_pk_bf16_f32 v131, v128, v129
	v_cvt_pk_bf16_f32 v132, v122, v123
	v_cvt_pk_bf16_f32 v133, v124, v125
	global_store_dwordx4 v[136:137], v[130:133], off nt
	s_mov_b64 s[14:15], 0x20000
	s_nop 0
	v_cvt_pk_bf16_f32 v130, v118, v119
	v_cvt_pk_bf16_f32 v131, v120, v121
	v_cvt_pk_bf16_f32 v132, v114, v115
	v_cvt_pk_bf16_f32 v133, v116, v117
	global_store_dwordx4 v[136:137], v[130:133], off offset:256 nt
	s_nop 1
	v_or_b32_e32 v130, 16, v174
	v_ashrrev_i32_e32 v131, 31, v130
	v_lshlrev_b64 v[130:131], 10, v[130:131]
	v_lshl_add_u64 v[138:139], v[134:135], 0, v[130:131]
	v_cvt_pk_bf16_f32 v130, v110, v111
	v_cvt_pk_bf16_f32 v131, v112, v113
	v_cvt_pk_bf16_f32 v132, v106, v107
	v_cvt_pk_bf16_f32 v133, v108, v109
	global_store_dwordx4 v[138:139], v[130:133], off nt
	s_nop 1
	v_cvt_pk_bf16_f32 v130, v102, v103
	v_cvt_pk_bf16_f32 v131, v104, v105
	v_cvt_pk_bf16_f32 v132, v98, v99
	v_cvt_pk_bf16_f32 v133, v100, v101
	global_store_dwordx4 v[138:139], v[130:133], off offset:256 nt
	s_nop 1
	v_or_b32_e32 v130, 32, v174
	v_ashrrev_i32_e32 v131, 31, v130
	v_lshlrev_b64 v[130:131], 10, v[130:131]
	v_lshl_add_u64 v[138:139], v[134:135], 0, v[130:131]
	v_cvt_pk_bf16_f32 v130, v94, v95
	v_cvt_pk_bf16_f32 v131, v96, v97
	v_cvt_pk_bf16_f32 v132, v90, v91
	v_cvt_pk_bf16_f32 v133, v92, v93
	global_store_dwordx4 v[138:139], v[130:133], off nt
	s_nop 1
	v_cvt_pk_bf16_f32 v130, v86, v87
	v_cvt_pk_bf16_f32 v131, v88, v89
	v_cvt_pk_bf16_f32 v132, v82, v83
	v_cvt_pk_bf16_f32 v133, v84, v85
	global_store_dwordx4 v[138:139], v[130:133], off offset:256 nt
	v_add_co_u32_e32 v138, vcc, s46, v136
	s_nop 0
	v_or_b32_e32 v130, 48, v174
	v_ashrrev_i32_e32 v131, 31, v130
	v_lshlrev_b64 v[130:131], 10, v[130:131]
	v_lshl_add_u64 v[134:135], v[134:135], 0, v[130:131]
	v_cvt_pk_bf16_f32 v130, v78, v79
	v_cvt_pk_bf16_f32 v131, v80, v81
	v_cvt_pk_bf16_f32 v132, v74, v75
	v_cvt_pk_bf16_f32 v133, v76, v77
	global_store_dwordx4 v[134:135], v[130:133], off nt
	v_addc_co_u32_e32 v139, vcc, 0, v137, vcc
	s_nop 0
	v_cvt_pk_bf16_f32 v130, v70, v71
	v_cvt_pk_bf16_f32 v131, v72, v73
	v_cvt_pk_bf16_f32 v132, v66, v67
	v_cvt_pk_bf16_f32 v133, v68, v69
	global_store_dwordx4 v[134:135], v[130:133], off offset:256 nt
	v_lshl_add_u64 v[134:135], v[136:137], 0, s[14:15]
	s_mov_b64 s[14:15], 0x24000
	v_cvt_pk_bf16_f32 v130, v62, v63
	v_cvt_pk_bf16_f32 v131, v64, v65
	v_cvt_pk_bf16_f32 v132, v58, v59
	v_cvt_pk_bf16_f32 v133, v60, v61
	global_store_dwordx4 v[138:139], v[130:133], off nt
	v_add_co_u32_e32 v138, vcc, s47, v136
	s_nop 0
	v_cvt_pk_bf16_f32 v130, v54, v55
	v_cvt_pk_bf16_f32 v131, v56, v57
	v_cvt_pk_bf16_f32 v132, v50, v51
	v_cvt_pk_bf16_f32 v133, v52, v53
	global_store_dwordx4 v[134:135], v[130:133], off offset:256 nt
	v_addc_co_u32_e32 v139, vcc, 0, v137, vcc
	s_nop 0
	v_cvt_pk_bf16_f32 v130, v46, v47
	v_cvt_pk_bf16_f32 v131, v48, v49
	v_cvt_pk_bf16_f32 v132, v42, v43
	v_cvt_pk_bf16_f32 v133, v44, v45
	v_lshl_add_u64 v[134:135], v[136:137], 0, s[14:15]
	global_store_dwordx4 v[138:139], v[130:133], off nt
	v_add_co_u32_e32 v138, vcc, s40, v136
	s_nop 0
	v_cvt_pk_bf16_f32 v130, v38, v39
	v_cvt_pk_bf16_f32 v131, v40, v41
	v_cvt_pk_bf16_f32 v132, v34, v35
	v_cvt_pk_bf16_f32 v133, v36, v37
	global_store_dwordx4 v[134:135], v[130:133], off offset:256 nt
	v_addc_co_u32_e32 v139, vcc, 0, v137, vcc
	s_nop 0
	v_cvt_pk_bf16_f32 v130, v30, v31
	v_cvt_pk_bf16_f32 v131, v32, v33
	v_cvt_pk_bf16_f32 v132, v26, v27
	v_cvt_pk_bf16_f32 v133, v28, v29
	v_lshl_add_u64 v[134:135], v[136:137], 0, s[18:19]
	global_store_dwordx4 v[138:139], v[130:133], off nt
	s_nop 1
	v_cvt_pk_bf16_f32 v130, v22, v23
	v_cvt_pk_bf16_f32 v131, v24, v25
	v_cvt_pk_bf16_f32 v132, v18, v19
	v_cvt_pk_bf16_f32 v133, v20, v21
	global_store_dwordx4 v[134:135], v[130:133], off offset:256 nt
	v_lshl_add_u64 v[134:135], v[136:137], 0, s[20:21]
	v_add_co_u32_e32 v136, vcc, s8, v136
	v_cvt_pk_bf16_f32 v130, v14, v15
	v_cvt_pk_bf16_f32 v131, v16, v17
	v_cvt_pk_bf16_f32 v132, v10, v11
	v_cvt_pk_bf16_f32 v133, v12, v13
	v_addc_co_u32_e32 v137, vcc, 0, v137, vcc
	global_store_dwordx4 v[136:137], v[130:133], off nt
	s_nop 1
	v_cvt_pk_bf16_f32 v130, v6, v7
	v_cvt_pk_bf16_f32 v131, v8, v9
	v_cvt_pk_bf16_f32 v132, v2, v3
	v_cvt_pk_bf16_f32 v133, v4, v5
	global_store_dwordx4 v[134:135], v[130:133], off offset:256 nt

.LBB0_201:
	s_andn2_b64 vcc, exec, s[34:35]
	s_cbranch_vccnz .LBB0_203
	v_mul_f32_e32 v134, 0xbfb8aa3b, v126
	v_mul_f32_e32 v135, 0xbfb8aa3b, v127
	v_exp_f32_e32 v134, v134
	v_exp_f32_e32 v135, v135
	s_cmp_lt_u32 s12, 6
	s_mov_b32 s14, 0x9800400
	v_add_f32_e32 v134, 1.0, v134
	v_add_f32_e32 v135, 1.0, v135
	v_rcp_f32_e32 v134, v134
	v_rcp_f32_e32 v135, v135
	s_cselect_b32 s14, s14, 0xb800400
	s_add_u32 s14, s62, s14
	s_addc_u32 s15, s63, 0
	v_pk_mul_f32 v[134:135], v[126:127], v[134:135]
	s_lshl_b32 s16, s12, 9
	v_cvt_pk_bf16_f32 v134, v134, v135
	v_mul_f32_e32 v135, 0xbfb8aa3b, v128
	v_exp_f32_e32 v135, v135
	s_and_b32 s16, s16, 0x200
	s_add_u32 s14, s14, s16
	s_addc_u32 s15, s15, 0
	v_add_f32_e32 v135, 1.0, v135
	v_rcp_f32_e32 v136, v135
	v_mul_f32_e32 v135, 0xbfb8aa3b, v129
	v_exp_f32_e32 v135, v135
	v_lshlrev_b32_e32 v158, 1, v160
	v_ashrrev_i32_e32 v175, 31, v174
	v_lshl_add_u64 v[132:133], s[14:15], 0, v[158:159]
	v_add_f32_e32 v135, 1.0, v135
	v_rcp_f32_e32 v137, v135
	v_lshlrev_b64 v[130:131], 10, v[174:175]
	v_lshl_add_u64 v[130:131], v[132:133], 0, v[130:131]
	s_mov_b64 s[14:15], 0x20000
	v_pk_mul_f32 v[136:137], v[128:129], v[136:137]
	s_nop 0
	v_cvt_pk_bf16_f32 v135, v136, v137
	v_mul_f32_e32 v136, 0xbfb8aa3b, v122
	v_mul_f32_e32 v137, 0xbfb8aa3b, v123
	v_exp_f32_e32 v136, v136
	v_exp_f32_e32 v137, v137
	v_add_f32_e32 v136, 1.0, v136
	v_add_f32_e32 v137, 1.0, v137
	v_rcp_f32_e32 v136, v136
	v_rcp_f32_e32 v137, v137
	s_nop 0
	v_pk_mul_f32 v[136:137], v[122:123], v[136:137]
	s_nop 0
	v_cvt_pk_bf16_f32 v136, v136, v137
	v_mul_f32_e32 v137, 0xbfb8aa3b, v124
	v_exp_f32_e32 v137, v137
	s_nop 0
	v_add_f32_e32 v137, 1.0, v137
	v_rcp_f32_e32 v138, v137
	v_mul_f32_e32 v137, 0xbfb8aa3b, v125
	v_exp_f32_e32 v137, v137
	s_nop 0
	v_add_f32_e32 v137, 1.0, v137
	v_rcp_f32_e32 v139, v137
	s_nop 0
	v_pk_mul_f32 v[138:139], v[124:125], v[138:139]
	s_nop 0
	v_cvt_pk_bf16_f32 v137, v138, v139
	global_store_dwordx4 v[130:131], v[134:137], off nt
	s_nop 1
	v_mul_f32_e32 v134, 0xbfb8aa3b, v118
	v_mul_f32_e32 v135, 0xbfb8aa3b, v119
	v_exp_f32_e32 v134, v134
	v_exp_f32_e32 v135, v135
	v_add_f32_e32 v134, 1.0, v134
	v_add_f32_e32 v135, 1.0, v135
	v_rcp_f32_e32 v134, v134
	v_rcp_f32_e32 v135, v135
	s_nop 0
	v_pk_mul_f32 v[134:135], v[118:119], v[134:135]
	s_nop 0
	v_cvt_pk_bf16_f32 v134, v134, v135
	v_mul_f32_e32 v135, 0xbfb8aa3b, v120
	v_exp_f32_e32 v135, v135
	s_nop 0
	v_add_f32_e32 v135, 1.0, v135
	v_rcp_f32_e32 v136, v135
	v_mul_f32_e32 v135, 0xbfb8aa3b, v121
	v_exp_f32_e32 v135, v135
	s_nop 0
	v_add_f32_e32 v135, 1.0, v135
	v_rcp_f32_e32 v137, v135
	s_nop 0
	v_pk_mul_f32 v[136:137], v[120:121], v[136:137]
	s_nop 0
	v_cvt_pk_bf16_f32 v135, v136, v137
	v_mul_f32_e32 v136, 0xbfb8aa3b, v114
	v_mul_f32_e32 v137, 0xbfb8aa3b, v115
	v_exp_f32_e32 v136, v136
	v_exp_f32_e32 v137, v137
	v_add_f32_e32 v136, 1.0, v136
	v_add_f32_e32 v137, 1.0, v137
	v_rcp_f32_e32 v136, v136
	v_rcp_f32_e32 v137, v137
	s_nop 0
	v_pk_mul_f32 v[136:137], v[114:115], v[136:137]
	s_nop 0
	v_cvt_pk_bf16_f32 v136, v136, v137
	v_mul_f32_e32 v137, 0xbfb8aa3b, v116
	v_exp_f32_e32 v137, v137
	s_nop 0
	v_add_f32_e32 v137, 1.0, v137
	v_rcp_f32_e32 v138, v137
	v_mul_f32_e32 v137, 0xbfb8aa3b, v117
	v_exp_f32_e32 v137, v137
	s_nop 0
	v_add_f32_e32 v137, 1.0, v137
	v_rcp_f32_e32 v139, v137
	s_nop 0
	v_pk_mul_f32 v[138:139], v[116:117], v[138:139]
	s_nop 0
	v_cvt_pk_bf16_f32 v137, v138, v139
	global_store_dwordx4 v[130:131], v[134:137], off offset:256 nt
	s_nop 1
	v_mul_f32_e32 v136, 0xbfb8aa3b, v110
	v_mul_f32_e32 v137, 0xbfb8aa3b, v111
	v_exp_f32_e32 v136, v136
	v_exp_f32_e32 v137, v137
	v_or_b32_e32 v134, 16, v174
	v_ashrrev_i32_e32 v135, 31, v134
	v_add_f32_e32 v136, 1.0, v136
	v_add_f32_e32 v137, 1.0, v137
	v_rcp_f32_e32 v136, v136
	v_rcp_f32_e32 v137, v137
	v_lshlrev_b64 v[134:135], 10, v[134:135]
	v_lshl_add_u64 v[134:135], v[132:133], 0, v[134:135]
	v_pk_mul_f32 v[136:137], v[110:111], v[136:137]
	s_nop 0
	v_cvt_pk_bf16_f32 v136, v136, v137
	v_mul_f32_e32 v137, 0xbfb8aa3b, v112
	v_exp_f32_e32 v137, v137
	s_nop 0
	v_add_f32_e32 v137, 1.0, v137
	v_rcp_f32_e32 v138, v137
	v_mul_f32_e32 v137, 0xbfb8aa3b, v113
	v_exp_f32_e32 v137, v137
	s_nop 0
	v_add_f32_e32 v137, 1.0, v137
	v_rcp_f32_e32 v139, v137
	s_nop 0
	v_pk_mul_f32 v[138:139], v[112:113], v[138:139]
	s_nop 0
	v_cvt_pk_bf16_f32 v137, v138, v139
	v_mul_f32_e32 v138, 0xbfb8aa3b, v106
	v_mul_f32_e32 v139, 0xbfb8aa3b, v107
	v_exp_f32_e32 v138, v138
	v_exp_f32_e32 v139, v139
	v_add_f32_e32 v138, 1.0, v138
	v_add_f32_e32 v139, 1.0, v139
	v_rcp_f32_e32 v138, v138
	v_rcp_f32_e32 v139, v139
	s_nop 0
	v_pk_mul_f32 v[138:139], v[106:107], v[138:139]
	s_nop 0
	v_cvt_pk_bf16_f32 v138, v138, v139
	v_mul_f32_e32 v139, 0xbfb8aa3b, v108
	v_exp_f32_e32 v139, v139
	s_nop 0
	v_add_f32_e32 v139, 1.0, v139
	v_rcp_f32_e32 v140, v139
	v_mul_f32_e32 v139, 0xbfb8aa3b, v109
	v_exp_f32_e32 v139, v139
	s_nop 0
	v_add_f32_e32 v139, 1.0, v139
	v_rcp_f32_e32 v141, v139
	s_nop 0
	v_pk_mul_f32 v[140:141], v[108:109], v[140:141]
	s_nop 0
	v_cvt_pk_bf16_f32 v139, v140, v141
	global_store_dwordx4 v[134:135], v[136:139], off nt
	s_nop 1
	v_mul_f32_e32 v136, 0xbfb8aa3b, v102
	v_mul_f32_e32 v137, 0xbfb8aa3b, v103
	v_exp_f32_e32 v136, v136
	v_exp_f32_e32 v137, v137
	v_add_f32_e32 v136, 1.0, v136
	v_add_f32_e32 v137, 1.0, v137
	v_rcp_f32_e32 v136, v136
	v_rcp_f32_e32 v137, v137
	s_nop 0
	v_pk_mul_f32 v[136:137], v[102:103], v[136:137]
	s_nop 0
	v_cvt_pk_bf16_f32 v136, v136, v137
	v_mul_f32_e32 v137, 0xbfb8aa3b, v104
	v_exp_f32_e32 v137, v137
	s_nop 0
	v_add_f32_e32 v137, 1.0, v137
	v_rcp_f32_e32 v138, v137
	v_mul_f32_e32 v137, 0xbfb8aa3b, v105
	v_exp_f32_e32 v137, v137
	s_nop 0
	v_add_f32_e32 v137, 1.0, v137
	v_rcp_f32_e32 v139, v137
	s_nop 0
	v_pk_mul_f32 v[138:139], v[104:105], v[138:139]
	s_nop 0
	v_cvt_pk_bf16_f32 v137, v138, v139
	v_mul_f32_e32 v138, 0xbfb8aa3b, v98
	v_mul_f32_e32 v139, 0xbfb8aa3b, v99
	v_exp_f32_e32 v138, v138
	v_exp_f32_e32 v139, v139
	v_add_f32_e32 v138, 1.0, v138
	v_add_f32_e32 v139, 1.0, v139
	v_rcp_f32_e32 v138, v138
	v_rcp_f32_e32 v139, v139
	s_nop 0
	v_pk_mul_f32 v[138:139], v[98:99], v[138:139]
	s_nop 0
	v_cvt_pk_bf16_f32 v138, v138, v139
	v_mul_f32_e32 v139, 0xbfb8aa3b, v100
	v_exp_f32_e32 v139, v139
	s_nop 0
	v_add_f32_e32 v139, 1.0, v139
	v_rcp_f32_e32 v140, v139
	v_mul_f32_e32 v139, 0xbfb8aa3b, v101
	v_exp_f32_e32 v139, v139
	s_nop 0
	v_add_f32_e32 v139, 1.0, v139
	v_rcp_f32_e32 v141, v139
	s_nop 0
	v_pk_mul_f32 v[140:141], v[100:101], v[140:141]
	s_nop 0
	v_cvt_pk_bf16_f32 v139, v140, v141
	global_store_dwordx4 v[134:135], v[136:139], off offset:256 nt
	v_or_b32_e32 v134, 32, v174
	v_ashrrev_i32_e32 v135, 31, v134
	v_mul_f32_e32 v136, 0xbfb8aa3b, v94
	v_mul_f32_e32 v137, 0xbfb8aa3b, v95
	v_exp_f32_e32 v136, v136
	v_exp_f32_e32 v137, v137
	v_lshlrev_b64 v[134:135], 10, v[134:135]
	v_lshl_add_u64 v[134:135], v[132:133], 0, v[134:135]
	v_add_f32_e32 v136, 1.0, v136
	v_add_f32_e32 v137, 1.0, v137
	v_rcp_f32_e32 v136, v136
	v_rcp_f32_e32 v137, v137
	s_nop 0
	v_pk_mul_f32 v[136:137], v[94:95], v[136:137]
	s_nop 0
	v_cvt_pk_bf16_f32 v136, v136, v137
	v_mul_f32_e32 v137, 0xbfb8aa3b, v96
	v_exp_f32_e32 v137, v137
	s_nop 0
	v_add_f32_e32 v137, 1.0, v137
	v_rcp_f32_e32 v138, v137
	v_mul_f32_e32 v137, 0xbfb8aa3b, v97
	v_exp_f32_e32 v137, v137
	s_nop 0
	v_add_f32_e32 v137, 1.0, v137
	v_rcp_f32_e32 v139, v137
	s_nop 0
	v_pk_mul_f32 v[138:139], v[96:97], v[138:139]
	s_nop 0
	v_cvt_pk_bf16_f32 v137, v138, v139
	v_mul_f32_e32 v138, 0xbfb8aa3b, v90
	v_mul_f32_e32 v139, 0xbfb8aa3b, v91
	v_exp_f32_e32 v138, v138
	v_exp_f32_e32 v139, v139
	v_add_f32_e32 v138, 1.0, v138
	v_add_f32_e32 v139, 1.0, v139
	v_rcp_f32_e32 v138, v138
	v_rcp_f32_e32 v139, v139
	s_nop 0
	v_pk_mul_f32 v[138:139], v[90:91], v[138:139]
	s_nop 0
	v_cvt_pk_bf16_f32 v138, v138, v139
	v_mul_f32_e32 v139, 0xbfb8aa3b, v92
	v_exp_f32_e32 v139, v139
	s_nop 0
	v_add_f32_e32 v139, 1.0, v139
	v_rcp_f32_e32 v140, v139
	v_mul_f32_e32 v139, 0xbfb8aa3b, v93
	v_exp_f32_e32 v139, v139
	s_nop 0
	v_add_f32_e32 v139, 1.0, v139
	v_rcp_f32_e32 v141, v139
	s_nop 0
	v_pk_mul_f32 v[140:141], v[92:93], v[140:141]
	s_nop 0
	v_cvt_pk_bf16_f32 v139, v140, v141
	global_store_dwordx4 v[134:135], v[136:139], off nt
	s_nop 1
	v_mul_f32_e32 v136, 0xbfb8aa3b, v86
	v_mul_f32_e32 v137, 0xbfb8aa3b, v87
	v_exp_f32_e32 v136, v136
	v_exp_f32_e32 v137, v137
	v_add_f32_e32 v136, 1.0, v136
	v_add_f32_e32 v137, 1.0, v137
	v_rcp_f32_e32 v136, v136
	v_rcp_f32_e32 v137, v137
	s_nop 0
	v_pk_mul_f32 v[136:137], v[86:87], v[136:137]
	s_nop 0
	v_cvt_pk_bf16_f32 v136, v136, v137
	v_mul_f32_e32 v137, 0xbfb8aa3b, v88
	v_exp_f32_e32 v137, v137
	s_nop 0
	v_add_f32_e32 v137, 1.0, v137
	v_rcp_f32_e32 v138, v137
	v_mul_f32_e32 v137, 0xbfb8aa3b, v89
	v_exp_f32_e32 v137, v137
	s_nop 0
	v_add_f32_e32 v137, 1.0, v137
	v_rcp_f32_e32 v139, v137
	s_nop 0
	v_pk_mul_f32 v[138:139], v[88:89], v[138:139]
	s_nop 0
	v_cvt_pk_bf16_f32 v137, v138, v139
	v_mul_f32_e32 v138, 0xbfb8aa3b, v82
	v_mul_f32_e32 v139, 0xbfb8aa3b, v83
	v_exp_f32_e32 v138, v138
	v_exp_f32_e32 v139, v139
	v_add_f32_e32 v138, 1.0, v138
	v_add_f32_e32 v139, 1.0, v139
	v_rcp_f32_e32 v138, v138
	v_rcp_f32_e32 v139, v139
	s_nop 0
	v_pk_mul_f32 v[138:139], v[82:83], v[138:139]
	s_nop 0
	v_cvt_pk_bf16_f32 v138, v138, v139
	v_mul_f32_e32 v139, 0xbfb8aa3b, v84
	v_exp_f32_e32 v139, v139
	s_nop 0
	v_add_f32_e32 v139, 1.0, v139
	v_rcp_f32_e32 v140, v139
	v_mul_f32_e32 v139, 0xbfb8aa3b, v85
	v_exp_f32_e32 v139, v139
	s_nop 0
	v_add_f32_e32 v139, 1.0, v139
	v_rcp_f32_e32 v141, v139
	s_nop 0
	v_pk_mul_f32 v[140:141], v[84:85], v[140:141]
	s_nop 0
	v_cvt_pk_bf16_f32 v139, v140, v141
	global_store_dwordx4 v[134:135], v[136:139], off offset:256 nt
	v_or_b32_e32 v134, 48, v174
	v_ashrrev_i32_e32 v135, 31, v134
	v_lshlrev_b64 v[134:135], 10, v[134:135]
	v_lshl_add_u64 v[132:133], v[132:133], 0, v[134:135]
	v_mul_f32_e32 v134, 0xbfb8aa3b, v78
	v_mul_f32_e32 v135, 0xbfb8aa3b, v79
	v_exp_f32_e32 v134, v134
	v_exp_f32_e32 v135, v135
	v_add_f32_e32 v134, 1.0, v134
	v_add_f32_e32 v135, 1.0, v135
	v_rcp_f32_e32 v134, v134
	v_rcp_f32_e32 v135, v135
	s_nop 0
	v_pk_mul_f32 v[134:135], v[78:79], v[134:135]
	s_nop 0
	v_cvt_pk_bf16_f32 v134, v134, v135
	v_mul_f32_e32 v135, 0xbfb8aa3b, v80
	v_exp_f32_e32 v135, v135
	s_nop 0
	v_add_f32_e32 v135, 1.0, v135
	v_rcp_f32_e32 v136, v135
	v_mul_f32_e32 v135, 0xbfb8aa3b, v81
	v_exp_f32_e32 v135, v135
	s_nop 0
	v_add_f32_e32 v135, 1.0, v135
	v_rcp_f32_e32 v137, v135
	s_nop 0
	v_pk_mul_f32 v[136:137], v[80:81], v[136:137]
	s_nop 0
	v_cvt_pk_bf16_f32 v135, v136, v137
	v_mul_f32_e32 v136, 0xbfb8aa3b, v74
	v_mul_f32_e32 v137, 0xbfb8aa3b, v75
	v_exp_f32_e32 v136, v136
	v_exp_f32_e32 v137, v137
	v_add_f32_e32 v136, 1.0, v136
	v_add_f32_e32 v137, 1.0, v137
	v_rcp_f32_e32 v136, v136
	v_rcp_f32_e32 v137, v137
	s_nop 0
	v_pk_mul_f32 v[136:137], v[74:75], v[136:137]
	s_nop 0
	v_cvt_pk_bf16_f32 v136, v136, v137
	v_mul_f32_e32 v137, 0xbfb8aa3b, v76
	v_exp_f32_e32 v137, v137
	s_nop 0
	v_add_f32_e32 v137, 1.0, v137
	v_rcp_f32_e32 v138, v137
	v_mul_f32_e32 v137, 0xbfb8aa3b, v77
	v_exp_f32_e32 v137, v137
	s_nop 0
	v_add_f32_e32 v137, 1.0, v137
	v_rcp_f32_e32 v139, v137
	s_nop 0
	v_pk_mul_f32 v[138:139], v[76:77], v[138:139]
	s_nop 0
	v_cvt_pk_bf16_f32 v137, v138, v139
	global_store_dwordx4 v[132:133], v[134:137], off nt
	s_nop 1
	v_mul_f32_e32 v134, 0xbfb8aa3b, v70
	v_mul_f32_e32 v135, 0xbfb8aa3b, v71
	v_exp_f32_e32 v134, v134
	v_exp_f32_e32 v135, v135
	v_add_f32_e32 v134, 1.0, v134
	v_add_f32_e32 v135, 1.0, v135
	v_rcp_f32_e32 v134, v134
	v_rcp_f32_e32 v135, v135
	s_nop 0
	v_pk_mul_f32 v[134:135], v[70:71], v[134:135]
	s_nop 0
	v_cvt_pk_bf16_f32 v134, v134, v135
	v_mul_f32_e32 v135, 0xbfb8aa3b, v72
	v_exp_f32_e32 v135, v135
	s_nop 0
	v_add_f32_e32 v135, 1.0, v135
	v_rcp_f32_e32 v136, v135
	v_mul_f32_e32 v135, 0xbfb8aa3b, v73
	v_exp_f32_e32 v135, v135
	s_nop 0
	v_add_f32_e32 v135, 1.0, v135
	v_rcp_f32_e32 v137, v135
	s_nop 0
	v_pk_mul_f32 v[136:137], v[72:73], v[136:137]
	s_nop 0
	v_cvt_pk_bf16_f32 v135, v136, v137
	v_mul_f32_e32 v136, 0xbfb8aa3b, v66
	v_mul_f32_e32 v137, 0xbfb8aa3b, v67
	v_exp_f32_e32 v136, v136
	v_exp_f32_e32 v137, v137
	v_add_f32_e32 v136, 1.0, v136
	v_add_f32_e32 v137, 1.0, v137
	v_rcp_f32_e32 v136, v136
	v_rcp_f32_e32 v137, v137
	s_nop 0
	v_pk_mul_f32 v[136:137], v[66:67], v[136:137]
	s_nop 0
	v_cvt_pk_bf16_f32 v136, v136, v137
	v_mul_f32_e32 v137, 0xbfb8aa3b, v68
	v_exp_f32_e32 v137, v137
	s_nop 0
	v_add_f32_e32 v137, 1.0, v137
	v_rcp_f32_e32 v138, v137
	v_mul_f32_e32 v137, 0xbfb8aa3b, v69
	v_exp_f32_e32 v137, v137
	s_nop 0
	v_add_f32_e32 v137, 1.0, v137
	v_rcp_f32_e32 v139, v137
	s_nop 0
	v_pk_mul_f32 v[138:139], v[68:69], v[138:139]
	s_nop 0
	v_cvt_pk_bf16_f32 v137, v138, v139
	global_store_dwordx4 v[132:133], v[134:137], off offset:256 nt
	v_lshl_add_u64 v[132:133], v[130:131], 0, s[14:15]
	s_mov_b64 s[14:15], 0x24000
	v_mul_f32_e32 v134, 0xbfb8aa3b, v62
	v_mul_f32_e32 v135, 0xbfb8aa3b, v63
	v_exp_f32_e32 v134, v134
	v_exp_f32_e32 v135, v135
	v_add_f32_e32 v134, 1.0, v134
	v_add_f32_e32 v135, 1.0, v135
	v_rcp_f32_e32 v134, v134
	v_rcp_f32_e32 v135, v135
	s_nop 0
	v_pk_mul_f32 v[134:135], v[62:63], v[134:135]
	s_nop 0
	v_cvt_pk_bf16_f32 v134, v134, v135
	v_mul_f32_e32 v135, 0xbfb8aa3b, v64
	v_exp_f32_e32 v135, v135
	s_nop 0
	v_add_f32_e32 v135, 1.0, v135
	v_rcp_f32_e32 v136, v135
	v_mul_f32_e32 v135, 0xbfb8aa3b, v65
	v_exp_f32_e32 v135, v135
	s_nop 0
	v_add_f32_e32 v135, 1.0, v135
	v_rcp_f32_e32 v137, v135
	s_nop 0
	v_pk_mul_f32 v[136:137], v[64:65], v[136:137]
	s_nop 0
	v_cvt_pk_bf16_f32 v135, v136, v137
	v_mul_f32_e32 v136, 0xbfb8aa3b, v58
	v_mul_f32_e32 v137, 0xbfb8aa3b, v59
	v_exp_f32_e32 v136, v136
	v_exp_f32_e32 v137, v137
	v_add_f32_e32 v136, 1.0, v136
	v_add_f32_e32 v137, 1.0, v137
	v_rcp_f32_e32 v136, v136
	v_rcp_f32_e32 v137, v137
	s_nop 0
	v_pk_mul_f32 v[136:137], v[58:59], v[136:137]
	s_nop 0
	v_cvt_pk_bf16_f32 v136, v136, v137
	v_mul_f32_e32 v137, 0xbfb8aa3b, v60
	v_exp_f32_e32 v137, v137
	s_nop 0
	v_add_f32_e32 v137, 1.0, v137
	v_rcp_f32_e32 v138, v137
	v_mul_f32_e32 v137, 0xbfb8aa3b, v61
	v_exp_f32_e32 v137, v137
	s_nop 0
	v_add_f32_e32 v137, 1.0, v137
	v_rcp_f32_e32 v139, v137
	s_nop 0
	v_pk_mul_f32 v[138:139], v[60:61], v[138:139]
	s_nop 0
	v_cvt_pk_bf16_f32 v137, v138, v139
	v_add_co_u32_e32 v138, vcc, s46, v130
	s_nop 1
	v_addc_co_u32_e32 v139, vcc, 0, v131, vcc
	global_store_dwordx4 v[138:139], v[134:137], off nt
	s_nop 1
	v_mul_f32_e32 v134, 0xbfb8aa3b, v54
	v_mul_f32_e32 v135, 0xbfb8aa3b, v55
	v_exp_f32_e32 v134, v134
	v_exp_f32_e32 v135, v135
	v_add_f32_e32 v134, 1.0, v134
	v_add_f32_e32 v135, 1.0, v135
	v_rcp_f32_e32 v134, v134
	v_rcp_f32_e32 v135, v135
	s_nop 0
	v_pk_mul_f32 v[134:135], v[54:55], v[134:135]
	s_nop 0
	v_cvt_pk_bf16_f32 v134, v134, v135
	v_mul_f32_e32 v135, 0xbfb8aa3b, v56
	v_exp_f32_e32 v135, v135
	s_nop 0
	v_add_f32_e32 v135, 1.0, v135
	v_rcp_f32_e32 v136, v135
	v_mul_f32_e32 v135, 0xbfb8aa3b, v57
	v_exp_f32_e32 v135, v135
	s_nop 0
	v_add_f32_e32 v135, 1.0, v135
	v_rcp_f32_e32 v137, v135
	s_nop 0
	v_pk_mul_f32 v[136:137], v[56:57], v[136:137]
	s_nop 0
	v_cvt_pk_bf16_f32 v135, v136, v137
	v_mul_f32_e32 v136, 0xbfb8aa3b, v50
	v_mul_f32_e32 v137, 0xbfb8aa3b, v51
	v_exp_f32_e32 v136, v136
	v_exp_f32_e32 v137, v137
	v_add_f32_e32 v136, 1.0, v136
	v_add_f32_e32 v137, 1.0, v137
	v_rcp_f32_e32 v136, v136
	v_rcp_f32_e32 v137, v137
	s_nop 0
	v_pk_mul_f32 v[136:137], v[50:51], v[136:137]
	s_nop 0
	v_cvt_pk_bf16_f32 v136, v136, v137
	v_mul_f32_e32 v137, 0xbfb8aa3b, v52
	v_exp_f32_e32 v137, v137
	s_nop 0
	v_add_f32_e32 v137, 1.0, v137
	v_rcp_f32_e32 v138, v137
	v_mul_f32_e32 v137, 0xbfb8aa3b, v53
	v_exp_f32_e32 v137, v137
	s_nop 0
	v_add_f32_e32 v137, 1.0, v137
	v_rcp_f32_e32 v139, v137
	s_nop 0
	v_pk_mul_f32 v[138:139], v[52:53], v[138:139]
	s_nop 0
	v_cvt_pk_bf16_f32 v137, v138, v139
	global_store_dwordx4 v[132:133], v[134:137], off offset:256 nt
	v_lshl_add_u64 v[132:133], v[130:131], 0, s[14:15]
	s_nop 0
	v_mul_f32_e32 v134, 0xbfb8aa3b, v46
	v_mul_f32_e32 v135, 0xbfb8aa3b, v47
	v_exp_f32_e32 v134, v134
	v_exp_f32_e32 v135, v135
	v_add_f32_e32 v134, 1.0, v134
	v_add_f32_e32 v135, 1.0, v135
	v_rcp_f32_e32 v134, v134
	v_rcp_f32_e32 v135, v135
	s_nop 0
	v_pk_mul_f32 v[134:135], v[46:47], v[134:135]
	s_nop 0
	v_cvt_pk_bf16_f32 v134, v134, v135
	v_mul_f32_e32 v135, 0xbfb8aa3b, v48
	v_exp_f32_e32 v135, v135
	s_nop 0
	v_add_f32_e32 v135, 1.0, v135
	v_rcp_f32_e32 v136, v135
	v_mul_f32_e32 v135, 0xbfb8aa3b, v49
	v_exp_f32_e32 v135, v135
	s_nop 0
	v_add_f32_e32 v135, 1.0, v135
	v_rcp_f32_e32 v137, v135
	s_nop 0
	v_pk_mul_f32 v[136:137], v[48:49], v[136:137]
	s_nop 0
	v_cvt_pk_bf16_f32 v135, v136, v137
	v_mul_f32_e32 v136, 0xbfb8aa3b, v42
	v_mul_f32_e32 v137, 0xbfb8aa3b, v43
	v_exp_f32_e32 v136, v136
	v_exp_f32_e32 v137, v137
	v_add_f32_e32 v136, 1.0, v136
	v_add_f32_e32 v137, 1.0, v137
	v_rcp_f32_e32 v136, v136
	v_rcp_f32_e32 v137, v137
	s_nop 0
	v_pk_mul_f32 v[136:137], v[42:43], v[136:137]
	s_nop 0
	v_cvt_pk_bf16_f32 v136, v136, v137
	v_mul_f32_e32 v137, 0xbfb8aa3b, v44
	v_exp_f32_e32 v137, v137
	s_nop 0
	v_add_f32_e32 v137, 1.0, v137
	v_rcp_f32_e32 v138, v137
	v_mul_f32_e32 v137, 0xbfb8aa3b, v45
	v_exp_f32_e32 v137, v137
	s_nop 0
	v_add_f32_e32 v137, 1.0, v137
	v_rcp_f32_e32 v139, v137
	s_nop 0
	v_pk_mul_f32 v[138:139], v[44:45], v[138:139]
	s_nop 0
	v_cvt_pk_bf16_f32 v137, v138, v139
	v_add_co_u32_e32 v138, vcc, s47, v130
	s_nop 1
	v_addc_co_u32_e32 v139, vcc, 0, v131, vcc
	global_store_dwordx4 v[138:139], v[134:137], off nt
	s_nop 1
	v_mul_f32_e32 v134, 0xbfb8aa3b, v38
	v_mul_f32_e32 v135, 0xbfb8aa3b, v39
	v_exp_f32_e32 v134, v134
	v_exp_f32_e32 v135, v135
	v_add_f32_e32 v134, 1.0, v134
	v_add_f32_e32 v135, 1.0, v135
	v_rcp_f32_e32 v134, v134
	v_rcp_f32_e32 v135, v135
	s_nop 0
	v_pk_mul_f32 v[134:135], v[38:39], v[134:135]
	s_nop 0
	v_cvt_pk_bf16_f32 v134, v134, v135
	v_mul_f32_e32 v135, 0xbfb8aa3b, v40
	v_exp_f32_e32 v135, v135
	s_nop 0
	v_add_f32_e32 v135, 1.0, v135
	v_rcp_f32_e32 v136, v135
	v_mul_f32_e32 v135, 0xbfb8aa3b, v41
	v_exp_f32_e32 v135, v135
	s_nop 0
	v_add_f32_e32 v135, 1.0, v135
	v_rcp_f32_e32 v137, v135
	s_nop 0
	v_pk_mul_f32 v[136:137], v[40:41], v[136:137]
	s_nop 0
	v_cvt_pk_bf16_f32 v135, v136, v137
	v_mul_f32_e32 v136, 0xbfb8aa3b, v34
	v_mul_f32_e32 v137, 0xbfb8aa3b, v35
	v_exp_f32_e32 v136, v136
	v_exp_f32_e32 v137, v137
	v_add_f32_e32 v136, 1.0, v136
	v_add_f32_e32 v137, 1.0, v137
	v_rcp_f32_e32 v136, v136
	v_rcp_f32_e32 v137, v137
	s_nop 0
	v_pk_mul_f32 v[136:137], v[34:35], v[136:137]
	s_nop 0
	v_cvt_pk_bf16_f32 v136, v136, v137
	v_mul_f32_e32 v137, 0xbfb8aa3b, v36
	v_exp_f32_e32 v137, v137
	s_nop 0
	v_add_f32_e32 v137, 1.0, v137
	v_rcp_f32_e32 v138, v137
	v_mul_f32_e32 v137, 0xbfb8aa3b, v37
	v_exp_f32_e32 v137, v137
	s_nop 0
	v_add_f32_e32 v137, 1.0, v137
	v_rcp_f32_e32 v139, v137
	s_nop 0
	v_pk_mul_f32 v[138:139], v[36:37], v[138:139]
	s_nop 0
	v_cvt_pk_bf16_f32 v137, v138, v139
	global_store_dwordx4 v[132:133], v[134:137], off offset:256 nt
	v_lshl_add_u64 v[132:133], v[130:131], 0, s[18:19]
	s_nop 0
	v_mul_f32_e32 v134, 0xbfb8aa3b, v30
	v_mul_f32_e32 v135, 0xbfb8aa3b, v31
	v_exp_f32_e32 v134, v134
	v_exp_f32_e32 v135, v135
	v_add_f32_e32 v134, 1.0, v134
	v_add_f32_e32 v135, 1.0, v135
	v_rcp_f32_e32 v134, v134
	v_rcp_f32_e32 v135, v135
	s_nop 0
	v_pk_mul_f32 v[134:135], v[30:31], v[134:135]
	s_nop 0
	v_cvt_pk_bf16_f32 v134, v134, v135
	v_mul_f32_e32 v135, 0xbfb8aa3b, v32
	v_exp_f32_e32 v135, v135
	s_nop 0
	v_add_f32_e32 v135, 1.0, v135
	v_rcp_f32_e32 v136, v135
	v_mul_f32_e32 v135, 0xbfb8aa3b, v33
	v_exp_f32_e32 v135, v135
	s_nop 0
	v_add_f32_e32 v135, 1.0, v135
	v_rcp_f32_e32 v137, v135
	s_nop 0
	v_pk_mul_f32 v[136:137], v[32:33], v[136:137]
	s_nop 0
	v_cvt_pk_bf16_f32 v135, v136, v137
	v_mul_f32_e32 v136, 0xbfb8aa3b, v26
	v_mul_f32_e32 v137, 0xbfb8aa3b, v27
	v_exp_f32_e32 v136, v136
	v_exp_f32_e32 v137, v137
	v_add_f32_e32 v136, 1.0, v136
	v_add_f32_e32 v137, 1.0, v137
	v_rcp_f32_e32 v136, v136
	v_rcp_f32_e32 v137, v137
	s_nop 0
	v_pk_mul_f32 v[136:137], v[26:27], v[136:137]
	s_nop 0
	v_cvt_pk_bf16_f32 v136, v136, v137
	v_mul_f32_e32 v137, 0xbfb8aa3b, v28
	v_exp_f32_e32 v137, v137
	s_nop 0
	v_add_f32_e32 v137, 1.0, v137
	v_rcp_f32_e32 v138, v137
	v_mul_f32_e32 v137, 0xbfb8aa3b, v29
	v_exp_f32_e32 v137, v137
	s_nop 0
	v_add_f32_e32 v137, 1.0, v137
	v_rcp_f32_e32 v139, v137
	s_nop 0
	v_pk_mul_f32 v[138:139], v[28:29], v[138:139]
	s_nop 0
	v_cvt_pk_bf16_f32 v137, v138, v139
	v_add_co_u32_e32 v138, vcc, s40, v130
	s_nop 1
	v_addc_co_u32_e32 v139, vcc, 0, v131, vcc
	global_store_dwordx4 v[138:139], v[134:137], off nt
	s_nop 1
	v_mul_f32_e32 v134, 0xbfb8aa3b, v22
	v_mul_f32_e32 v135, 0xbfb8aa3b, v23
	v_exp_f32_e32 v134, v134
	v_exp_f32_e32 v135, v135
	v_add_f32_e32 v134, 1.0, v134
	v_add_f32_e32 v135, 1.0, v135
	v_rcp_f32_e32 v134, v134
	v_rcp_f32_e32 v135, v135
	s_nop 0
	v_pk_mul_f32 v[134:135], v[22:23], v[134:135]
	s_nop 0
	v_cvt_pk_bf16_f32 v134, v134, v135
	v_mul_f32_e32 v135, 0xbfb8aa3b, v24
	v_exp_f32_e32 v135, v135
	s_nop 0
	v_add_f32_e32 v135, 1.0, v135
	v_rcp_f32_e32 v136, v135
	v_mul_f32_e32 v135, 0xbfb8aa3b, v25
	v_exp_f32_e32 v135, v135
	s_nop 0
	v_add_f32_e32 v135, 1.0, v135
	v_rcp_f32_e32 v137, v135
	s_nop 0
	v_pk_mul_f32 v[136:137], v[24:25], v[136:137]
	s_nop 0
	v_cvt_pk_bf16_f32 v135, v136, v137
	v_mul_f32_e32 v136, 0xbfb8aa3b, v18
	v_mul_f32_e32 v137, 0xbfb8aa3b, v19
	v_exp_f32_e32 v136, v136
	v_exp_f32_e32 v137, v137
	v_add_f32_e32 v136, 1.0, v136
	v_add_f32_e32 v137, 1.0, v137
	v_rcp_f32_e32 v136, v136
	v_rcp_f32_e32 v137, v137
	s_nop 0
	v_pk_mul_f32 v[136:137], v[18:19], v[136:137]
	s_nop 0
	v_cvt_pk_bf16_f32 v136, v136, v137
	v_mul_f32_e32 v137, 0xbfb8aa3b, v20
	v_exp_f32_e32 v137, v137
	s_nop 0
	v_add_f32_e32 v137, 1.0, v137
	v_rcp_f32_e32 v138, v137
	v_mul_f32_e32 v137, 0xbfb8aa3b, v21
	v_exp_f32_e32 v137, v137
	s_nop 0
	v_add_f32_e32 v137, 1.0, v137
	v_rcp_f32_e32 v139, v137
	s_nop 0
	v_pk_mul_f32 v[138:139], v[20:21], v[138:139]
	s_nop 0
	v_cvt_pk_bf16_f32 v137, v138, v139
	global_store_dwordx4 v[132:133], v[134:137], off offset:256 nt
	v_lshl_add_u64 v[132:133], v[130:131], 0, s[20:21]
	v_add_co_u32_e32 v130, vcc, s8, v130
	v_mul_f32_e32 v134, 0xbfb8aa3b, v14
	v_mul_f32_e32 v135, 0xbfb8aa3b, v15
	v_exp_f32_e32 v134, v134
	v_exp_f32_e32 v135, v135
	v_addc_co_u32_e32 v131, vcc, 0, v131, vcc
	v_add_f32_e32 v134, 1.0, v134
	v_add_f32_e32 v135, 1.0, v135
	v_rcp_f32_e32 v134, v134
	v_rcp_f32_e32 v135, v135
	s_nop 0
	v_pk_mul_f32 v[134:135], v[14:15], v[134:135]
	s_nop 0
	v_cvt_pk_bf16_f32 v134, v134, v135
	v_mul_f32_e32 v135, 0xbfb8aa3b, v16
	v_exp_f32_e32 v135, v135
	s_nop 0
	v_add_f32_e32 v135, 1.0, v135
	v_rcp_f32_e32 v136, v135
	v_mul_f32_e32 v135, 0xbfb8aa3b, v17
	v_exp_f32_e32 v135, v135
	s_nop 0
	v_add_f32_e32 v135, 1.0, v135
	v_rcp_f32_e32 v137, v135
	s_nop 0
	v_pk_mul_f32 v[136:137], v[16:17], v[136:137]
	s_nop 0
	v_cvt_pk_bf16_f32 v135, v136, v137
	v_mul_f32_e32 v136, 0xbfb8aa3b, v10
	v_mul_f32_e32 v137, 0xbfb8aa3b, v11
	v_exp_f32_e32 v136, v136
	v_exp_f32_e32 v137, v137
	v_add_f32_e32 v136, 1.0, v136
	v_add_f32_e32 v137, 1.0, v137
	v_rcp_f32_e32 v136, v136
	v_rcp_f32_e32 v137, v137
	s_nop 0
	v_pk_mul_f32 v[136:137], v[10:11], v[136:137]
	s_nop 0
	v_cvt_pk_bf16_f32 v136, v136, v137
	v_mul_f32_e32 v137, 0xbfb8aa3b, v12
	v_exp_f32_e32 v137, v137
	s_nop 0
	v_add_f32_e32 v137, 1.0, v137
	v_rcp_f32_e32 v138, v137
	v_mul_f32_e32 v137, 0xbfb8aa3b, v13
	v_exp_f32_e32 v137, v137
	s_nop 0
	v_add_f32_e32 v137, 1.0, v137
	v_rcp_f32_e32 v139, v137
	s_nop 0
	v_pk_mul_f32 v[138:139], v[12:13], v[138:139]
	s_nop 0
	v_cvt_pk_bf16_f32 v137, v138, v139
	global_store_dwordx4 v[130:131], v[134:137], off nt
	v_mul_f32_e32 v130, 0xbfb8aa3b, v6
	v_mul_f32_e32 v131, 0xbfb8aa3b, v7
	v_exp_f32_e32 v130, v130
	v_exp_f32_e32 v131, v131
	v_add_f32_e32 v130, 1.0, v130
	v_add_f32_e32 v131, 1.0, v131
	v_rcp_f32_e32 v130, v130
	v_rcp_f32_e32 v131, v131
	s_nop 0
	v_pk_mul_f32 v[130:131], v[6:7], v[130:131]
	s_nop 0
	v_cvt_pk_bf16_f32 v134, v130, v131
	v_mul_f32_e32 v130, 0xbfb8aa3b, v8
	v_mul_f32_e32 v131, 0xbfb8aa3b, v9
	v_exp_f32_e32 v130, v130
	v_exp_f32_e32 v131, v131
	v_add_f32_e32 v130, 1.0, v130
	v_add_f32_e32 v131, 1.0, v131
	v_rcp_f32_e32 v130, v130
	v_rcp_f32_e32 v131, v131
	s_nop 0
	v_pk_mul_f32 v[130:131], v[8:9], v[130:131]
	s_nop 0
	v_cvt_pk_bf16_f32 v135, v130, v131
	v_mul_f32_e32 v130, 0xbfb8aa3b, v2
	v_mul_f32_e32 v131, 0xbfb8aa3b, v3
	v_exp_f32_e32 v130, v130
	v_exp_f32_e32 v131, v131
	v_add_f32_e32 v130, 1.0, v130
	v_add_f32_e32 v131, 1.0, v131
	v_rcp_f32_e32 v130, v130
	v_rcp_f32_e32 v131, v131
	s_nop 0
	v_pk_mul_f32 v[130:131], v[2:3], v[130:131]
	s_nop 0
	v_cvt_pk_bf16_f32 v136, v130, v131
	v_mul_f32_e32 v130, 0xbfb8aa3b, v4
	v_mul_f32_e32 v131, 0xbfb8aa3b, v5
	v_exp_f32_e32 v130, v130
	v_exp_f32_e32 v131, v131
	v_add_f32_e32 v130, 1.0, v130
	v_add_f32_e32 v131, 1.0, v131
	v_rcp_f32_e32 v130, v130
	v_rcp_f32_e32 v131, v131
	s_nop 0
	v_pk_mul_f32 v[130:131], v[4:5], v[130:131]
	s_nop 0
	v_cvt_pk_bf16_f32 v137, v130, v131
	global_store_dwordx4 v[132:133], v[134:137], off offset:256 nt

.LBB0_204:
	s_andn2_b64 vcc, exec, s[34:35]
	s_cbranch_vccnz .LBB0_184
	v_mul_f32_e32 v134, v127, v127
	v_fmac_f32_e32 v134, v126, v126
	v_fmac_f32_e32 v134, v128, v128
	v_fmac_f32_e32 v134, v129, v129
	v_fmac_f32_e32 v134, v122, v122
	v_cvt_pk_bf16_f32 v126, v126, v127
	v_cvt_pk_bf16_f32 v127, v128, v129
	v_cvt_pk_bf16_f32 v128, v122, v123
	v_mul_f32_e32 v122, v119, v119
	v_fmac_f32_e32 v122, v118, v118
	v_fmac_f32_e32 v122, v120, v120
	v_fmac_f32_e32 v122, v121, v121
	s_lshl_b32 s14, s12, 8
	v_fmac_f32_e32 v122, v114, v114
	s_ashr_i32 s15, s14, 31
	v_fmac_f32_e32 v134, v123, v123
	v_fmac_f32_e32 v122, v115, v115
	s_lshl_b64 s[14:15], s[14:15], 1
	v_fmac_f32_e32 v134, v124, v124
	v_fmac_f32_e32 v122, v116, v116
	s_add_u32 s14, s87, s14
	v_fmac_f32_e32 v134, v125, v125
	v_fmac_f32_e32 v122, v117, v117
	s_addc_u32 s15, s92, s15
	v_add_f32_e32 v122, v134, v122
	s_cmp_eq_u32 s12, 3
	v_cvt_pk_bf16_f32 v118, v118, v119
	v_cvt_pk_bf16_f32 v119, v120, v121
	v_cvt_pk_bf16_f32 v120, v114, v115
	v_mov_b32_e32 v114, v122
	s_cselect_b32 s16, 0x20000, 0
	s_movk_i32 s12, 0x100
	v_permlane16_swap_b32_e32 v122, v114
	s_cselect_b32 s12, s12, 0x300
	s_cselect_b32 s15, s94, s15
	s_cselect_b32 s14, s93, s14
	s_add_u32 s30, s95, s16
	v_lshlrev_b32_e32 v158, 1, v160
	v_cvt_pk_bf16_f32 v121, v116, v117
	v_add_f32_e32 v116, v122, v114
	s_addc_u32 s31, s96, 0
	v_lshl_add_u64 v[130:131], s[14:15], 0, v[158:159]
	v_ashrrev_i32_e32 v175, 31, v174
	v_mad_i64_i32 v[132:133], s[14:15], s12, v174, 0
	v_mov_b32_e32 v117, v116
	v_lshl_add_u64 v[132:133], v[132:133], 1, v[130:131]
	v_cvt_pk_bf16_f32 v129, v124, v125
	v_permlane32_swap_b32_e32 v116, v117
	v_lshl_add_u64 v[114:115], v[174:175], 2, s[30:31]
	global_store_dwordx4 v[132:133], v[126:129], off nt
	global_store_dwordx4 v[132:133], v[118:121], off offset:256 nt
	s_and_saveexec_b64 s[30:31], s[2:3]
	s_cbranch_execz .LBB0_207
	v_add_f32_e32 v116, v116, v117
	global_atomic_add_f32 v[114:115], v116, off
.LBB0_207:
	s_or_b64 exec, exec, s[30:31]
	v_mul_f32_e32 v118, v111, v111
	v_fmac_f32_e32 v118, v110, v110
	v_fmac_f32_e32 v118, v112, v112
	v_fmac_f32_e32 v118, v113, v113
	v_fmac_f32_e32 v118, v106, v106
	v_cvt_pk_bf16_f32 v110, v110, v111
	v_cvt_pk_bf16_f32 v111, v112, v113
	v_cvt_pk_bf16_f32 v112, v106, v107
	v_mul_f32_e32 v106, v103, v103
	v_fmac_f32_e32 v106, v102, v102
	v_fmac_f32_e32 v106, v104, v104
	v_fmac_f32_e32 v106, v105, v105
	v_fmac_f32_e32 v106, v98, v98
	v_fmac_f32_e32 v118, v107, v107
	v_fmac_f32_e32 v106, v99, v99
	v_fmac_f32_e32 v118, v108, v108
	v_fmac_f32_e32 v106, v100, v100
	v_fmac_f32_e32 v118, v109, v109
	v_fmac_f32_e32 v106, v101, v101
	v_add_f32_e32 v106, v118, v106
	v_cvt_pk_bf16_f32 v102, v102, v103
	v_cvt_pk_bf16_f32 v103, v104, v105
	v_cvt_pk_bf16_f32 v104, v98, v99
	v_mov_b32_e32 v98, v106
	s_nop 1
	v_permlane16_swap_b32_e32 v106, v98
	v_or_b32_e32 v116, 16, v174
	v_add_f32_e32 v98, v106, v98
	v_mad_i64_i32 v[116:117], s[14:15], s12, v116, 0
	v_mov_b32_e32 v99, v98
	v_lshl_add_u64 v[116:117], v[116:117], 1, v[130:131]
	v_cvt_pk_bf16_f32 v113, v108, v109
	v_cvt_pk_bf16_f32 v105, v100, v101
	v_permlane32_swap_b32_e32 v98, v99
	global_store_dwordx4 v[116:117], v[110:113], off nt
	global_store_dwordx4 v[116:117], v[102:105], off offset:256 nt
	s_and_saveexec_b64 s[30:31], s[2:3]
	s_cbranch_execz .LBB0_209
	v_add_f32_e32 v98, v98, v99
	global_atomic_add_f32 v[114:115], v98, off offset:64
.LBB0_209:
	s_or_b64 exec, exec, s[30:31]
	v_mul_f32_e32 v100, v95, v95
	v_fmac_f32_e32 v100, v94, v94
	v_fmac_f32_e32 v100, v96, v96
	v_fmac_f32_e32 v100, v97, v97
	v_fmac_f32_e32 v100, v90, v90
	v_cvt_pk_bf16_f32 v94, v94, v95
	v_cvt_pk_bf16_f32 v95, v96, v97
	v_cvt_pk_bf16_f32 v96, v90, v91
	v_mul_f32_e32 v90, v87, v87
	v_fmac_f32_e32 v90, v86, v86
	v_fmac_f32_e32 v90, v88, v88
	v_fmac_f32_e32 v90, v89, v89
	v_fmac_f32_e32 v90, v82, v82
	v_fmac_f32_e32 v100, v91, v91
	v_fmac_f32_e32 v90, v83, v83
	v_fmac_f32_e32 v100, v92, v92
	v_fmac_f32_e32 v90, v84, v84
	v_fmac_f32_e32 v100, v93, v93
	v_fmac_f32_e32 v90, v85, v85
	v_add_f32_e32 v90, v100, v90
	v_cvt_pk_bf16_f32 v86, v86, v87
	v_cvt_pk_bf16_f32 v87, v88, v89
	v_cvt_pk_bf16_f32 v88, v82, v83
	v_mov_b32_e32 v82, v90
	s_nop 1
	v_permlane16_swap_b32_e32 v90, v82
	v_or_b32_e32 v98, 32, v174
	v_add_f32_e32 v82, v90, v82
	v_mad_i64_i32 v[98:99], s[14:15], s12, v98, 0
	v_mov_b32_e32 v83, v82
	v_lshl_add_u64 v[98:99], v[98:99], 1, v[130:131]
	v_cvt_pk_bf16_f32 v97, v92, v93
	v_cvt_pk_bf16_f32 v89, v84, v85
	v_permlane32_swap_b32_e32 v82, v83
	global_store_dwordx4 v[98:99], v[94:97], off nt
	global_store_dwordx4 v[98:99], v[86:89], off offset:256 nt
	s_and_saveexec_b64 s[30:31], s[2:3]
	s_cbranch_execz .LBB0_211
	v_add_f32_e32 v82, v82, v83
	global_atomic_add_f32 v[114:115], v82, off offset:128
.LBB0_211:
	s_or_b64 exec, exec, s[30:31]
	v_mul_f32_e32 v84, v79, v79
	v_fmac_f32_e32 v84, v78, v78
	v_fmac_f32_e32 v84, v80, v80
	v_fmac_f32_e32 v84, v81, v81
	v_fmac_f32_e32 v84, v74, v74
	v_cvt_pk_bf16_f32 v78, v78, v79
	v_cvt_pk_bf16_f32 v79, v80, v81
	v_cvt_pk_bf16_f32 v80, v74, v75
	v_mul_f32_e32 v74, v71, v71
	v_fmac_f32_e32 v74, v70, v70
	v_fmac_f32_e32 v74, v72, v72
	v_fmac_f32_e32 v74, v73, v73
	v_fmac_f32_e32 v74, v66, v66
	v_fmac_f32_e32 v84, v75, v75
	v_fmac_f32_e32 v74, v67, v67
	v_fmac_f32_e32 v84, v76, v76
	v_fmac_f32_e32 v74, v68, v68
	v_fmac_f32_e32 v84, v77, v77
	v_fmac_f32_e32 v74, v69, v69
	v_add_f32_e32 v74, v84, v74
	v_cvt_pk_bf16_f32 v70, v70, v71
	v_cvt_pk_bf16_f32 v71, v72, v73
	v_cvt_pk_bf16_f32 v72, v66, v67
	v_mov_b32_e32 v66, v74
	s_nop 1
	v_permlane16_swap_b32_e32 v74, v66
	v_or_b32_e32 v82, 48, v174
	v_add_f32_e32 v66, v74, v66
	v_mad_i64_i32 v[82:83], s[14:15], s12, v82, 0
	v_mov_b32_e32 v67, v66
	v_lshl_add_u64 v[82:83], v[82:83], 1, v[130:131]
	v_cvt_pk_bf16_f32 v81, v76, v77
	v_cvt_pk_bf16_f32 v73, v68, v69
	v_permlane32_swap_b32_e32 v66, v67
	global_store_dwordx4 v[82:83], v[78:81], off nt
	global_store_dwordx4 v[82:83], v[70:73], off offset:256 nt
	s_and_saveexec_b64 s[30:31], s[2:3]
	s_cbranch_execz .LBB0_213
	v_add_f32_e32 v66, v66, v67
	global_atomic_add_f32 v[114:115], v66, off offset:192
.LBB0_213:
	s_or_b64 exec, exec, s[30:31]
	v_mul_f32_e32 v68, v63, v63
	v_fmac_f32_e32 v68, v62, v62
	v_fmac_f32_e32 v68, v64, v64
	v_fmac_f32_e32 v68, v65, v65
	v_fmac_f32_e32 v68, v58, v58
	v_cvt_pk_bf16_f32 v62, v62, v63
	v_cvt_pk_bf16_f32 v63, v64, v65
	v_cvt_pk_bf16_f32 v64, v58, v59
	v_mul_f32_e32 v58, v55, v55
	v_fmac_f32_e32 v58, v54, v54
	v_fmac_f32_e32 v58, v56, v56
	v_fmac_f32_e32 v58, v57, v57
	v_fmac_f32_e32 v58, v50, v50
	v_fmac_f32_e32 v68, v59, v59
	v_fmac_f32_e32 v58, v51, v51
	v_fmac_f32_e32 v68, v60, v60
	v_fmac_f32_e32 v58, v52, v52
	v_fmac_f32_e32 v68, v61, v61
	v_fmac_f32_e32 v58, v53, v53
	v_add_f32_e32 v58, v68, v58
	v_cvt_pk_bf16_f32 v54, v54, v55
	v_cvt_pk_bf16_f32 v55, v56, v57
	v_cvt_pk_bf16_f32 v56, v50, v51
	v_mov_b32_e32 v50, v58
	s_nop 1
	v_permlane16_swap_b32_e32 v58, v50
	v_add_u32_e32 v66, 0x80, v174
	v_add_f32_e32 v50, v58, v50
	v_mad_i64_i32 v[66:67], s[14:15], s12, v66, 0
	v_mov_b32_e32 v51, v50
	v_lshl_add_u64 v[66:67], v[66:67], 1, v[130:131]
	v_cvt_pk_bf16_f32 v65, v60, v61
	v_cvt_pk_bf16_f32 v57, v52, v53
	v_permlane32_swap_b32_e32 v50, v51
	global_store_dwordx4 v[66:67], v[62:65], off nt
	global_store_dwordx4 v[66:67], v[54:57], off offset:256 nt
	s_and_saveexec_b64 s[30:31], s[2:3]
	s_cbranch_execz .LBB0_215
	v_add_f32_e32 v50, v50, v51
	global_atomic_add_f32 v[114:115], v50, off offset:512
.LBB0_215:
	s_or_b64 exec, exec, s[30:31]
	v_mul_f32_e32 v52, v47, v47
	v_fmac_f32_e32 v52, v46, v46
	v_fmac_f32_e32 v52, v48, v48
	v_fmac_f32_e32 v52, v49, v49
	v_fmac_f32_e32 v52, v42, v42
	v_cvt_pk_bf16_f32 v46, v46, v47
	v_cvt_pk_bf16_f32 v47, v48, v49
	v_cvt_pk_bf16_f32 v48, v42, v43
	v_mul_f32_e32 v42, v39, v39
	v_fmac_f32_e32 v42, v38, v38
	v_fmac_f32_e32 v42, v40, v40
	v_fmac_f32_e32 v42, v41, v41
	v_fmac_f32_e32 v42, v34, v34
	v_fmac_f32_e32 v52, v43, v43
	v_fmac_f32_e32 v42, v35, v35
	v_fmac_f32_e32 v52, v44, v44
	v_fmac_f32_e32 v42, v36, v36
	v_fmac_f32_e32 v52, v45, v45
	v_fmac_f32_e32 v42, v37, v37
	v_add_f32_e32 v42, v52, v42
	v_cvt_pk_bf16_f32 v38, v38, v39
	v_cvt_pk_bf16_f32 v39, v40, v41
	v_cvt_pk_bf16_f32 v40, v34, v35
	v_mov_b32_e32 v34, v42
	s_nop 1
	v_permlane16_swap_b32_e32 v42, v34
	v_add_u32_e32 v50, 0x90, v174
	v_add_f32_e32 v34, v42, v34
	v_mad_i64_i32 v[50:51], s[14:15], s12, v50, 0
	v_mov_b32_e32 v35, v34
	v_lshl_add_u64 v[50:51], v[50:51], 1, v[130:131]
	v_cvt_pk_bf16_f32 v49, v44, v45
	v_cvt_pk_bf16_f32 v41, v36, v37
	v_permlane32_swap_b32_e32 v34, v35
	global_store_dwordx4 v[50:51], v[46:49], off nt
	global_store_dwordx4 v[50:51], v[38:41], off offset:256 nt
	s_and_saveexec_b64 s[30:31], s[2:3]
	s_cbranch_execz .LBB0_217
	v_add_f32_e32 v34, v34, v35
	global_atomic_add_f32 v[114:115], v34, off offset:576
.LBB0_217:
	s_or_b64 exec, exec, s[30:31]
	v_mul_f32_e32 v36, v31, v31
	v_fmac_f32_e32 v36, v30, v30
	v_fmac_f32_e32 v36, v32, v32
	v_fmac_f32_e32 v36, v33, v33
	v_fmac_f32_e32 v36, v26, v26
	v_cvt_pk_bf16_f32 v30, v30, v31
	v_cvt_pk_bf16_f32 v31, v32, v33
	v_cvt_pk_bf16_f32 v32, v26, v27
	v_mul_f32_e32 v26, v23, v23
	v_fmac_f32_e32 v26, v22, v22
	v_fmac_f32_e32 v26, v24, v24
	v_fmac_f32_e32 v26, v25, v25
	v_fmac_f32_e32 v26, v18, v18
	v_fmac_f32_e32 v36, v27, v27
	v_fmac_f32_e32 v26, v19, v19
	v_fmac_f32_e32 v36, v28, v28
	v_fmac_f32_e32 v26, v20, v20
	v_fmac_f32_e32 v36, v29, v29
	v_fmac_f32_e32 v26, v21, v21
	v_add_f32_e32 v26, v36, v26
	v_cvt_pk_bf16_f32 v22, v22, v23
	v_cvt_pk_bf16_f32 v23, v24, v25
	v_cvt_pk_bf16_f32 v24, v18, v19
	v_mov_b32_e32 v18, v26
	s_nop 1
	v_permlane16_swap_b32_e32 v26, v18
	v_add_u32_e32 v34, 0xa0, v174
	v_add_f32_e32 v18, v26, v18
	v_mad_i64_i32 v[34:35], s[14:15], s12, v34, 0
	v_mov_b32_e32 v19, v18
	v_lshl_add_u64 v[34:35], v[34:35], 1, v[130:131]
	v_cvt_pk_bf16_f32 v33, v28, v29
	v_cvt_pk_bf16_f32 v25, v20, v21
	v_permlane32_swap_b32_e32 v18, v19
	global_store_dwordx4 v[34:35], v[30:33], off nt
	global_store_dwordx4 v[34:35], v[22:25], off offset:256 nt
	s_and_saveexec_b64 s[30:31], s[2:3]
	s_cbranch_execz .LBB0_219
	v_add_f32_e32 v18, v18, v19
	global_atomic_add_f32 v[114:115], v18, off offset:640
.LBB0_219:
	s_or_b64 exec, exec, s[30:31]
	v_mul_f32_e32 v20, v15, v15
	v_fmac_f32_e32 v20, v14, v14
	v_fmac_f32_e32 v20, v16, v16
	v_fmac_f32_e32 v20, v17, v17
	v_fmac_f32_e32 v20, v10, v10
	v_cvt_pk_bf16_f32 v14, v14, v15
	v_cvt_pk_bf16_f32 v15, v16, v17
	v_cvt_pk_bf16_f32 v16, v10, v11
	v_mul_f32_e32 v10, v7, v7
	v_fmac_f32_e32 v10, v6, v6
	v_fmac_f32_e32 v10, v8, v8
	v_fmac_f32_e32 v10, v9, v9
	v_fmac_f32_e32 v10, v2, v2
	v_fmac_f32_e32 v20, v11, v11
	v_fmac_f32_e32 v10, v3, v3
	v_fmac_f32_e32 v20, v12, v12
	v_fmac_f32_e32 v10, v4, v4
	v_fmac_f32_e32 v20, v13, v13
	v_fmac_f32_e32 v10, v5, v5
	v_add_f32_e32 v10, v20, v10
	v_cvt_pk_bf16_f32 v6, v6, v7
	v_cvt_pk_bf16_f32 v7, v8, v9
	v_cvt_pk_bf16_f32 v8, v2, v3
	v_mov_b32_e32 v2, v10
	s_nop 1
	v_permlane16_swap_b32_e32 v10, v2
	v_add_u32_e32 v18, 0xb0, v174
	v_add_f32_e32 v2, v10, v2
	v_mad_i64_i32 v[18:19], s[14:15], s12, v18, 0
	v_mov_b32_e32 v3, v2
	v_lshl_add_u64 v[18:19], v[18:19], 1, v[130:131]
	v_cvt_pk_bf16_f32 v17, v12, v13
	v_cvt_pk_bf16_f32 v9, v4, v5
	v_permlane32_swap_b32_e32 v2, v3
	global_store_dwordx4 v[18:19], v[14:17], off nt
	global_store_dwordx4 v[18:19], v[6:9], off offset:256 nt
	s_and_saveexec_b64 s[30:31], s[2:3]
	s_cbranch_execz .LBB0_183
	v_add_f32_e32 v2, v2, v3
	global_atomic_add_f32 v[114:115], v2, off offset:704
	s_branch .LBB0_183
